# FFN1 main loops: pairs of pipeline phases merged (32 MFMA per barrier interval), LDS reads waited before barrier
# speedup vs baseline: 1.0068x; 1.0068x over previous
; __device__ __forceinline__ int otid() { int t = threadIdx.x; asm volatile("" : "+v"(t)); return t; }
; __device__ __forceinline__ void pool_phase(const bf16_t* hn, bf16_t* dd) {
;     for (int gid = blockIdx.x * NTHREADS + otid(); gid < (T / 32) * 128; gid += gridDim.x * NTHREADS) {
;         const int col8 = gid & 127, chunk = gid >> 7, w = 2 << (col8 >> 5), t0 = chunk * 32, pos0 = t0 & (SEQ - 1);
;         const bf16_t* hp = hn + (size_t)t0 * D + col8 * 8; bf16_t* dp = dd + (size_t)t0 * D + col8 * 8;
;         float s[8];
; #pragma unroll
;         for (int i = 0; i < 8; ++i) s[i] = 0.f;
;         if (pos0) for (int k = 1; k <= w; ++k) { float v[8]; ld8(hp - (size_t)k * D, v);
.LBB0_85:
	s_or_b64 exec, exec, s[4:5]
	s_waitcnt lgkmcnt(0)
	v_mov_b32_e32 v0, v219
	s_barrier
	s_mov_b32 s3, 0x20000
	v_lshl_add_u32 v28, s2, 9, v0
	v_cmp_gt_i32_e32 vcc, s3, v28
	s_and_saveexec_b64 s[4:5], vcc
	s_cbranch_execz .LBB0_98
	v_and_b32_e32 v1, 0x7f, v0
	v_bfe_u32 v0, v0, 5, 2
	v_lshlrev_b32_e64 v29, v0, 2
	v_lshlrev_b32_e32 v4, 4, v1
	v_mov_b32_e32 v5, 0
	v_lshl_add_u64 v[0:1], s[54:55], 0, v[4:5]
	v_lshlrev_b32_e32 v5, 11, v29
	s_mov_b64 s[6:7], 0x5fff800
	v_sub_co_u32_e32 v4, vcc, v4, v5
	v_lshl_add_u64 v[2:3], v[0:1], 0, s[6:7]
	s_nop 0
	v_subb_co_u32_e64 v5, s[6:7], 0, 0, vcc
	v_lshl_add_u64 v[4:5], s[54:55], 0, v[4:5]
	s_mov_b64 s[6:7], 0x6000000
	s_movk_i32 s10, 0xf800
	s_lshl_b32 s3, s50, 9
	v_lshl_add_u64 v[4:5], v[4:5], 0, s[6:7]
	s_mov_b64 s[8:9], 0
	s_mov_b32 s11, -1
	s_mov_b32 s6, 0x1ffff
	s_branch .LBB0_88

; __device__ __forceinline__ void xcd_barrier(const XcdBarrier& b) {
;     asm volatile("s_waitcnt vmcnt(0) lgkmcnt(0)" ::: "memory");
;     __syncthreads();
;     if (threadIdx.x == 0) {
;         unsigned* bar = b.bar;
;         __builtin_amdgcn_s_waitcnt(0);
;         unsigned nloc = b.st[0], nx = b.st[1];
;         if (nloc == 0u) { xcd_barrier_complete(bar, b.x, nloc, nx); b.st[0] = nloc; b.st[1] = nx; }
; __device__ __forceinline__ void pool_phase(const bf16_t* hn, bf16_t* dd) {
;     ...
;         for (int i = 0; i < 32; ++i) {
;             float cur[8]; ld8(hp + (size_t)i * D, cur); const int pos = pos0 + i;
; #pragma unroll
;             for (int q = 0; q < 8; ++q) s[q] += cur[q];
;             if (pos >= w) { float v[8]; ld8(hp + (size_t)(i - w) * D, v);
; #pragma unroll
;                 for (int q = 0; q < 8; ++q) s[q] -= v[q]; }
.LBB0_96:
	v_lshl_add_u64 v[18:19], v[16:17], 0, s[12:13]
	v_add_co_u32_e32 v20, vcc, 0x6000000, v18
	s_nop 1
	v_addc_co_u32_e32 v21, vcc, 0, v19, vcc
	global_load_dwordx4 v[24:27], v[20:21], off
	v_cmp_ge_u32_e32 vcc, v30, v29
	s_waitcnt vmcnt(0)
	v_lshlrev_b32_e32 v20, 16, v24
	v_and_b32_e32 v21, 0xffff0000, v24
	v_lshlrev_b32_e32 v22, 16, v25
	v_and_b32_e32 v23, 0xffff0000, v25
	v_lshlrev_b32_e32 v24, 16, v26
	v_and_b32_e32 v25, 0xffff0000, v26
	v_lshlrev_b32_e32 v26, 16, v27
	v_and_b32_e32 v27, 0xffff0000, v27
	v_pk_add_f32 v[8:9], v[8:9], v[20:21]
	v_pk_add_f32 v[10:11], v[10:11], v[22:23]
	v_pk_add_f32 v[12:13], v[12:13], v[24:25]
	v_pk_add_f32 v[6:7], v[6:7], v[26:27]
	s_and_saveexec_b64 s[14:15], vcc
	s_cbranch_execz .LBB0_95
	v_lshl_add_u64 v[32:33], v[14:15], 0, s[12:13]
	global_load_dwordx4 v[32:35], v[32:33], off
	s_waitcnt vmcnt(0)
	v_lshlrev_b32_e32 v36, 16, v32
	v_and_b32_e32 v37, 0xffff0000, v32
	v_lshlrev_b32_e32 v32, 16, v33
	v_and_b32_e32 v33, 0xffff0000, v33
	v_lshlrev_b32_e32 v38, 16, v34
	v_and_b32_e32 v39, 0xffff0000, v34
	v_lshlrev_b32_e32 v34, 16, v35
	v_and_b32_e32 v35, 0xffff0000, v35
	v_pk_add_f32 v[8:9], v[8:9], v[36:37] neg_lo:[0,1] neg_hi:[0,1]
	v_pk_add_f32 v[10:11], v[10:11], v[32:33] neg_lo:[0,1] neg_hi:[0,1]
	v_pk_add_f32 v[12:13], v[12:13], v[38:39] neg_lo:[0,1] neg_hi:[0,1]
	v_pk_add_f32 v[6:7], v[6:7], v[34:35] neg_lo:[0,1] neg_hi:[0,1]
	s_branch .LBB0_95
.LBB0_98:
	s_or_b64 exec, exec, s[4:5]
	s_waitcnt vmcnt(0) lgkmcnt(0)
	s_barrier
	s_mov_b64 s[4:5], exec
	v_readlane_b32 s6, v252, 0
	v_readlane_b32 s7, v252, 1
	s_and_b64 s[6:7], s[4:5], s[6:7]
	s_mov_b64 exec, s[6:7]
	s_cbranch_execz .LBB0_150
	s_add_i32 s3, 0, 0x23000
	v_mov_b32_e32 v0, s3
	s_waitcnt vmcnt(0) expcnt(0) lgkmcnt(0)
	ds_read_b32 v2, v0
	s_add_i32 s3, 0, 0x23004
	v_mov_b32_e32 v0, s3
	ds_read_b32 v0, v0
	s_waitcnt lgkmcnt(1)
	v_cmp_ne_u32_e32 vcc, 0, v2
	s_cbranch_vccnz .LBB0_114
	s_add_u32 s8, s54, 0x1000
	s_addc_u32 s9, s55, 0
	s_add_u32 s10, s54, 0x1100
	s_addc_u32 s11, s55, 0
	s_add_u32 s12, s54, 0x1200
	s_addc_u32 s13, s55, 0
	s_mul_i32 s3, s51, s96
	s_add_u32 s14, s54, 0x1300
	s_mul_i32 s3, s3, s50
	s_addc_u32 s15, s55, 0
	s_mov_b32 s6, 1
	v_mov_b32_e32 v16, 0
	s_branch .LBB0_102

; #define PG8_STAGE(bufoff, gbase, voff) do { _Pragma("unroll") for (int _i = 0; _i < 2; ++_i) \
;         __builtin_amdgcn_global_load_lds((const unsigned*)((const char*)(gbase) + (voff)[_i]), (LAS unsigned*)(lds + (bufoff) + ldsw + _i * 8192), 16, 0, 0); } while (0)
; #define PG8_LDA(dst, b, h) do { _Pragma("unroll") for (int m = 0; m < 4; ++m) _Pragma("unroll") for (int k = 0; k < 2; ++k) dst[m][k] = *(const LAS bf16x8*)(lds + PG8_SA(b, h) + aoff + m * 2048 + k * 1024); } while (0)
; #define PG8_LDB(dst, b, h) do { _Pragma("unroll") for (int n = 0; n < 2; ++n) _Pragma("unroll") for (int k = 0; k < 2; ++k) dst[n][k] = *(const LAS bf16x8*)(lds + PG8_SB(b, h) + boff + n * 2048 + k * 1024); } while (0)
; #define PG8_MMA(ai, bj, At, Bt) do { __builtin_amdgcn_s_setprio(1); _Pragma("unroll") for (int m = 0; m < 4; ++m) _Pragma("unroll") for (int n = 0; n < 2; ++n) _Pragma("unroll") for (int k = 0; k < 2; ++k) \
;         acc[ai][bj][m][n] = __builtin_amdgcn_mfma_f32_16x16x32_bf16(Bt[n][k], At[m][k], acc[ai][bj][m][n], 0, 0, 0); __builtin_amdgcn_s_setprio(0); } while (0)
; #define PG8_WAIT_V(n) asm volatile("s_waitcnt vmcnt(" #n ")" ::: "memory")
; #define PG8_WAIT_L(n) asm volatile("s_waitcnt lgkmcnt(" #n ")" ::: "memory")
; template <class Epi>
; __device__ __forceinline__ void gemm_phase(LAS unsigned char* lds, const Gemm g, const StaticOrder& S, const Epi& E) {
;     ...
;         for (int t = 0; t < nt; t += 2) {
;             const bool last = (t == nt - 2);
;             const char* a1 = cA + (size_t)(t + 1) * kstep;
;             const char* a2 = last ? nA : cA + (size_t)(t + 2) * kstep; const char* b2 = last ? nB : cB + (size_t)(t + 2) * kstep;
;             const char* a3 = a2 + kstep; const char* b3 = b2 + kstep;
;             PG8_LDB(B0, 0, 0); PG8_SCHED; PG8_LDA(At, 0, 0); PG8_STAGE(PG8_SA(1, 1), a1 + hstepA, voffA);
;             PG8_WAIT_L(8); PG8_BAR; PG8_WAIT_L(0); PG8_MMA(0, 0, At, B0); PG8_BAR; PG8_SCHED;
;             PG8_LDB(B1, 0, 1); PG8_STAGE(PG8_SB(0, 0), b2, voffB);
;             PG8_BAR; PG8_WAIT_L(0); PG8_MMA(0, 1, At, B1); PG8_BAR;
;             PG8_LDA(At, 0, 1); PG8_STAGE(PG8_SA(0, 0), a2, voffA);
;             PG8_BAR; PG8_WAIT_L(0); PG8_MMA(1, 0, At, B0); PG8_BAR; PG8_SCHED;
;             PG8_STAGE(PG8_SB(0, 1), b2 + hstepB, voffB);
;             PG8_WAIT_V(6); PG8_BAR; PG8_MMA(1, 1, At, B1); PG8_BAR;
.LBB0_309:
	ds_read_b128 v[96:99], v243
	ds_read_b128 v[100:103], v243 offset:1024
	ds_read_b128 v[104:107], v243 offset:2048
	ds_read_b128 v[108:111], v243 offset:3072
	s_add_u32 s38, s36, 0x100
	s_addc_u32 s39, s37, 0
	s_cmp_eq_u32 s79, 12
	s_cselect_b32 s43, s27, s39
	s_cselect_b32 s42, s75, s38
	s_cselect_b32 s41, s25, s78
	s_cselect_b32 s40, s76, s77
	v_lshl_add_u64 v[176:177], s[36:37], 0, v[224:225]
	s_add_i32 m0, s45, 0xc000
	ds_read_b128 v[112:115], v244
	ds_read_b128 v[116:119], v244 offset:1024
	ds_read_b128 v[120:123], v244 offset:2048
	ds_read_b128 v[124:127], v244 offset:3072
	ds_read_b128 v[160:163], v244 offset:4096
	ds_read_b128 v[164:167], v244 offset:5120
	ds_read_b128 v[168:171], v244 offset:6144
	ds_read_b128 v[172:175], v244 offset:7168
	global_load_lds_dwordx4 v[176:177], off
	v_lshl_add_u64 v[176:177], s[36:37], 0, v[226:227]
	s_add_i32 m0, s45, 0xe000
	s_nop 0
	global_load_lds_dwordx4 v[176:177], off
	ds_read_b128 v[176:179], v245
	ds_read_b128 v[180:183], v245 offset:1024
	ds_read_b128 v[184:187], v245 offset:2048
	ds_read_b128 v[188:191], v245 offset:3072
	s_waitcnt lgkmcnt(0)
	s_barrier
	s_setprio 1
	v_mfma_f32_16x16x32_bf16 v[156:159], v[96:99], v[112:115], v[156:159]
	v_mfma_f32_16x16x32_bf16 v[60:63], v[104:107], v[112:115], v[60:63]
	v_mfma_f32_16x16x32_bf16 v[144:147], v[96:99], v[120:123], v[144:147]
	v_mfma_f32_16x16x32_bf16 v[48:51], v[104:107], v[120:123], v[48:51]
	v_mfma_f32_16x16x32_bf16 v[136:139], v[96:99], v[160:163], v[136:139]
	v_mfma_f32_16x16x32_bf16 v[40:43], v[104:107], v[160:163], v[40:43]
	v_mfma_f32_16x16x32_bf16 v[148:151], v[96:99], v[168:171], v[148:151]
	v_mfma_f32_16x16x32_bf16 v[52:55], v[104:107], v[168:171], v[52:55]
	v_mfma_f32_16x16x32_bf16 v[156:159], v[100:103], v[116:119], v[156:159]
	v_mfma_f32_16x16x32_bf16 v[60:63], v[108:111], v[116:119], v[60:63]
	v_mfma_f32_16x16x32_bf16 v[144:147], v[100:103], v[124:127], v[144:147]
	v_mfma_f32_16x16x32_bf16 v[48:51], v[108:111], v[124:127], v[48:51]
	v_mfma_f32_16x16x32_bf16 v[136:139], v[100:103], v[164:167], v[136:139]
	v_mfma_f32_16x16x32_bf16 v[40:43], v[108:111], v[164:167], v[40:43]
	v_mfma_f32_16x16x32_bf16 v[148:151], v[100:103], v[172:175], v[148:151]
	v_mfma_f32_16x16x32_bf16 v[52:55], v[108:111], v[172:175], v[52:55]
	v_mfma_f32_16x16x32_bf16 v[152:155], v[176:179], v[112:115], v[152:155]
	v_mfma_f32_16x16x32_bf16 v[56:59], v[184:187], v[112:115], v[56:59]
	v_mfma_f32_16x16x32_bf16 v[36:39], v[184:187], v[120:123], v[36:39]
	v_mfma_f32_16x16x32_bf16 v[32:35], v[184:187], v[160:163], v[32:35]
	v_mfma_f32_16x16x32_bf16 v[44:47], v[184:187], v[168:171], v[44:47]
	v_mfma_f32_16x16x32_bf16 v[152:155], v[180:183], v[116:119], v[152:155]
	v_mfma_f32_16x16x32_bf16 v[56:59], v[188:191], v[116:119], v[56:59]
	v_mfma_f32_16x16x32_bf16 v[112:115], v[176:179], v[120:123], v[132:135]
	v_mfma_f32_16x16x32_bf16 v[36:39], v[188:191], v[124:127], v[36:39]
	v_mfma_f32_16x16x32_bf16 v[116:119], v[176:179], v[160:163], v[128:131]
	v_mfma_f32_16x16x32_bf16 v[32:35], v[188:191], v[164:167], v[32:35]
	v_mfma_f32_16x16x32_bf16 v[120:123], v[176:179], v[168:171], v[140:143]
	v_mfma_f32_16x16x32_bf16 v[44:47], v[188:191], v[172:175], v[44:47]
	v_mfma_f32_16x16x32_bf16 v[112:115], v[180:183], v[124:127], v[112:115]
	v_mfma_f32_16x16x32_bf16 v[116:119], v[180:183], v[164:167], v[116:119]
	v_mfma_f32_16x16x32_bf16 v[120:123], v[180:183], v[172:175], v[120:123]
	s_setprio 0
	s_barrier
	s_nop 1
	ds_read_b128 v[124:127], v244 offset:16384
	ds_read_b128 v[128:131], v244 offset:17408
	ds_read_b128 v[132:135], v244 offset:18432
	ds_read_b128 v[140:143], v244 offset:19456
	ds_read_b128 v[160:163], v244 offset:20480
	ds_read_b128 v[164:167], v244 offset:21504
	ds_read_b128 v[168:171], v244 offset:22528
	ds_read_b128 v[172:175], v244 offset:23552
	s_add_i32 s36, s72, s6
	v_lshl_add_u64 v[196:197], s[40:41], 0, v[214:215]
	s_mov_b32 m0, s36
	s_nop 0
	global_load_lds_dwordx4 v[196:197], off
	v_lshl_add_u64 v[198:199], s[40:41], 0, v[210:211]
	s_add_i32 m0, s36, 0x2000
	s_nop 0
	global_load_lds_dwordx4 v[198:199], off
	s_mov_b32 m0, s45
	v_lshl_add_u64 v[200:201], s[42:43], 0, v[216:217]
	global_load_lds_dwordx4 v[200:201], off
	v_lshl_add_u64 v[202:203], s[42:43], 0, v[212:213]
	s_mov_b32 m0, s46
	s_nop 0
	global_load_lds_dwordx4 v[202:203], off
	s_add_u32 s36, s40, 0x40000
	s_addc_u32 s37, s41, 0
	s_add_i32 s80, s73, s6
	v_lshl_add_u64 v[254:255], s[36:37], 0, v[214:215]
	s_mov_b32 m0, s80
	s_nop 0
	global_load_lds_dwordx4 v[254:255], off
	v_lshl_add_u64 v[254:255], s[36:37], 0, v[210:211]
	s_add_i32 m0, s80, 0x2000
	s_nop 0
	global_load_lds_dwordx4 v[254:255], off
	s_waitcnt vmcnt(6)
	s_waitcnt lgkmcnt(0)
	s_barrier
; #define PG8_STAGE(bufoff, gbase, voff) do { _Pragma("unroll") for (int _i = 0; _i < 2; ++_i) \
;         __builtin_amdgcn_global_load_lds((const unsigned*)((const char*)(gbase) + (voff)[_i]), (LAS unsigned*)(lds + (bufoff) + ldsw + _i * 8192), 16, 0, 0); } while (0)
; #define PG8_LDA(dst, b, h) do { _Pragma("unroll") for (int m = 0; m < 4; ++m) _Pragma("unroll") for (int k = 0; k < 2; ++k) dst[m][k] = *(const LAS bf16x8*)(lds + PG8_SA(b, h) + aoff + m * 2048 + k * 1024); } while (0)
; #define PG8_LDB(dst, b, h) do { _Pragma("unroll") for (int n = 0; n < 2; ++n) _Pragma("unroll") for (int k = 0; k < 2; ++k) dst[n][k] = *(const LAS bf16x8*)(lds + PG8_SB(b, h) + boff + n * 2048 + k * 1024); } while (0)
; #define PG8_MMA(ai, bj, At, Bt) do { __builtin_amdgcn_s_setprio(1); _Pragma("unroll") for (int m = 0; m < 4; ++m) _Pragma("unroll") for (int n = 0; n < 2; ++n) _Pragma("unroll") for (int k = 0; k < 2; ++k) \
;         acc[ai][bj][m][n] = __builtin_amdgcn_mfma_f32_16x16x32_bf16(Bt[n][k], At[m][k], acc[ai][bj][m][n], 0, 0, 0); __builtin_amdgcn_s_setprio(0); } while (0)
; #define PG8_WAIT_V(n) asm volatile("s_waitcnt vmcnt(" #n ")" ::: "memory")
; #define PG8_WAIT_L(n) asm volatile("s_waitcnt lgkmcnt(" #n ")" ::: "memory")
; #define PG8_BAR __builtin_amdgcn_s_barrier()
; #define PG8_SCHED __builtin_amdgcn_sched_barrier(0)
; template <class Epi>
; __device__ __forceinline__ void gemm_phase(LAS unsigned char* lds, const Gemm g, const StaticOrder& S, const Epi& E) {
;     ...
;             PG8_BAR; PG8_WAIT_L(0); PG8_MMA(1, 0, At, B0); PG8_BAR; PG8_SCHED;
;             PG8_STAGE(PG8_SB(0, 1), b2 + hstepB, voffB);
;             PG8_WAIT_V(6); PG8_BAR; PG8_MMA(1, 1, At, B1); PG8_BAR;
;             PG8_LDB(B0, 1, 0); PG8_SCHED; PG8_LDA(At, 1, 0); PG8_STAGE(PG8_SA(0, 1), a2 + hstepA, voffA);
;             PG8_WAIT_L(8); PG8_BAR; PG8_WAIT_L(0); PG8_MMA(0, 0, At, B0); PG8_BAR; PG8_SCHED;
;             PG8_LDB(B1, 1, 1); PG8_STAGE(PG8_SB(1, 0), b3, voffB);
;             PG8_BAR; PG8_WAIT_L(0); PG8_MMA(0, 1, At, B1); PG8_BAR;
	s_setprio 1
	v_mfma_f32_16x16x32_bf16 v[92:95], v[96:99], v[124:127], v[92:95]
	v_mfma_f32_16x16x32_bf16 v[28:31], v[104:107], v[124:127], v[28:31]
	v_mfma_f32_16x16x32_bf16 v[80:83], v[96:99], v[132:135], v[80:83]
	v_mfma_f32_16x16x32_bf16 v[16:19], v[104:107], v[132:135], v[16:19]
	v_mfma_f32_16x16x32_bf16 v[76:79], v[96:99], v[160:163], v[76:79]
	v_mfma_f32_16x16x32_bf16 v[12:15], v[104:107], v[160:163], v[12:15]
	v_mfma_f32_16x16x32_bf16 v[84:87], v[96:99], v[168:171], v[84:87]
	v_mfma_f32_16x16x32_bf16 v[20:23], v[104:107], v[168:171], v[20:23]
	v_mfma_f32_16x16x32_bf16 v[92:95], v[100:103], v[128:131], v[92:95]
	v_mfma_f32_16x16x32_bf16 v[28:31], v[108:111], v[128:131], v[28:31]
	v_mfma_f32_16x16x32_bf16 v[80:83], v[100:103], v[140:143], v[80:83]
	v_mfma_f32_16x16x32_bf16 v[16:19], v[108:111], v[140:143], v[16:19]
	v_mfma_f32_16x16x32_bf16 v[76:79], v[100:103], v[164:167], v[76:79]
	v_mfma_f32_16x16x32_bf16 v[12:15], v[108:111], v[164:167], v[12:15]
	v_mfma_f32_16x16x32_bf16 v[84:87], v[100:103], v[172:175], v[84:87]
	v_mfma_f32_16x16x32_bf16 v[20:23], v[108:111], v[172:175], v[20:23]
	v_mfma_f32_16x16x32_bf16 v[88:91], v[176:179], v[124:127], v[88:91]
	v_mfma_f32_16x16x32_bf16 v[24:27], v[184:187], v[124:127], v[24:27]
	v_mfma_f32_16x16x32_bf16 v[68:71], v[176:179], v[132:135], v[68:71]
	v_mfma_f32_16x16x32_bf16 v[4:7], v[184:187], v[132:135], v[4:7]
	v_mfma_f32_16x16x32_bf16 v[64:67], v[176:179], v[160:163], v[64:67]
	v_mfma_f32_16x16x32_bf16 v[0:3], v[184:187], v[160:163], v[0:3]
	v_mfma_f32_16x16x32_bf16 v[72:75], v[176:179], v[168:171], v[72:75]
	v_mfma_f32_16x16x32_bf16 v[8:11], v[184:187], v[168:171], v[8:11]
	v_mfma_f32_16x16x32_bf16 v[88:91], v[180:183], v[128:131], v[88:91]
	v_mfma_f32_16x16x32_bf16 v[24:27], v[188:191], v[128:131], v[24:27]
	v_mfma_f32_16x16x32_bf16 v[68:71], v[180:183], v[140:143], v[68:71]
	v_mfma_f32_16x16x32_bf16 v[4:7], v[188:191], v[140:143], v[4:7]
	v_mfma_f32_16x16x32_bf16 v[64:67], v[180:183], v[164:167], v[64:67]
	v_mfma_f32_16x16x32_bf16 v[0:3], v[188:191], v[164:167], v[0:3]
	v_mfma_f32_16x16x32_bf16 v[72:75], v[180:183], v[172:175], v[72:75]
	v_mfma_f32_16x16x32_bf16 v[8:11], v[188:191], v[172:175], v[8:11]
	s_setprio 0
	s_add_i32 s80, 0, 0x18000
	v_add_u32_e32 v108, s80, v235
	s_barrier
	ds_read_b128 v[96:99], v108
	ds_read_b128 v[100:103], v108 offset:1024
	ds_read_b128 v[104:107], v108 offset:2048
	ds_read_b128 v[108:111], v108 offset:3072
	s_add_u32 s36, s42, 0x40000
	s_addc_u32 s37, s43, 0
	s_mov_b32 m0, s47
	v_lshl_add_u64 v[132:133], s[36:37], 0, v[216:217]
	ds_read_b128 v[124:127], v244 offset:32768
	ds_read_b128 v[128:131], v244 offset:33792
	ds_read_b128 v[140:143], v244 offset:34816
	ds_read_b128 v[160:163], v244 offset:35840
	ds_read_b128 v[164:167], v244 offset:36864
	ds_read_b128 v[168:171], v244 offset:37888
	ds_read_b128 v[172:175], v244 offset:38912
	ds_read_b128 v[176:179], v244 offset:39936
	global_load_lds_dwordx4 v[132:133], off
	v_lshl_add_u64 v[132:133], s[36:37], 0, v[212:213]
	s_mov_b32 m0, s48
	s_nop 0
	global_load_lds_dwordx4 v[132:133], off
	s_add_i32 s42, 0, 0x1c000
	v_add_u32_e32 v132, s42, v235
	ds_read_b128 v[180:183], v132
	ds_read_b128 v[184:187], v132 offset:1024
	ds_read_b128 v[188:191], v132 offset:2048
	ds_read_b128 v[192:195], v132 offset:3072
	s_waitcnt lgkmcnt(0)
	s_barrier
	s_setprio 1
	v_mfma_f32_16x16x32_bf16 v[132:135], v[96:99], v[124:127], v[156:159]
	v_mfma_f32_16x16x32_bf16 v[156:159], v[100:103], v[128:131], v[132:135]
	v_mfma_f32_16x16x32_bf16 v[132:135], v[96:99], v[140:143], v[144:147]
	v_mfma_f32_16x16x32_bf16 v[144:147], v[100:103], v[160:163], v[132:135]
	v_mfma_f32_16x16x32_bf16 v[132:135], v[96:99], v[164:167], v[136:139]
	v_mfma_f32_16x16x32_bf16 v[60:63], v[104:107], v[124:127], v[60:63]
	v_mfma_f32_16x16x32_bf16 v[48:51], v[104:107], v[140:143], v[48:51]
	v_mfma_f32_16x16x32_bf16 v[136:139], v[100:103], v[168:171], v[132:135]
	v_mfma_f32_16x16x32_bf16 v[40:43], v[104:107], v[164:167], v[40:43]
	v_mfma_f32_16x16x32_bf16 v[132:135], v[96:99], v[172:175], v[148:151]
	v_mfma_f32_16x16x32_bf16 v[52:55], v[104:107], v[172:175], v[52:55]
	v_mfma_f32_16x16x32_bf16 v[60:63], v[108:111], v[128:131], v[60:63]
	v_mfma_f32_16x16x32_bf16 v[48:51], v[108:111], v[160:163], v[48:51]
	v_mfma_f32_16x16x32_bf16 v[40:43], v[108:111], v[168:171], v[40:43]
	v_mfma_f32_16x16x32_bf16 v[148:151], v[100:103], v[176:179], v[132:135]
	v_mfma_f32_16x16x32_bf16 v[52:55], v[108:111], v[176:179], v[52:55]
	v_mfma_f32_16x16x32_bf16 v[132:135], v[180:183], v[124:127], v[152:155]
	v_mfma_f32_16x16x32_bf16 v[112:115], v[180:183], v[140:143], v[112:115]
	v_mfma_f32_16x16x32_bf16 v[152:155], v[184:187], v[128:131], v[132:135]
	v_mfma_f32_16x16x32_bf16 v[56:59], v[188:191], v[124:127], v[56:59]
	v_mfma_f32_16x16x32_bf16 v[132:135], v[184:187], v[160:163], v[112:115]
	v_mfma_f32_16x16x32_bf16 v[112:115], v[180:183], v[164:167], v[116:119]
	v_mfma_f32_16x16x32_bf16 v[56:59], v[192:195], v[128:131], v[56:59]
	v_mfma_f32_16x16x32_bf16 v[36:39], v[188:191], v[140:143], v[36:39]
	v_mfma_f32_16x16x32_bf16 v[128:131], v[184:187], v[168:171], v[112:115]
	v_mfma_f32_16x16x32_bf16 v[32:35], v[188:191], v[164:167], v[32:35]
	v_mfma_f32_16x16x32_bf16 v[112:115], v[180:183], v[172:175], v[120:123]
	v_mfma_f32_16x16x32_bf16 v[44:47], v[188:191], v[172:175], v[44:47]
	v_mfma_f32_16x16x32_bf16 v[36:39], v[192:195], v[160:163], v[36:39]
	v_mfma_f32_16x16x32_bf16 v[32:35], v[192:195], v[168:171], v[32:35]
	v_mfma_f32_16x16x32_bf16 v[140:143], v[184:187], v[176:179], v[112:115]
	v_mfma_f32_16x16x32_bf16 v[44:47], v[192:195], v[176:179], v[44:47]
	s_setprio 0
	s_barrier
; #define LAS __attribute__((address_space(3)))
; #define PG8_STAGE(bufoff, gbase, voff) do { _Pragma("unroll") for (int _i = 0; _i < 2; ++_i) \
;         __builtin_amdgcn_global_load_lds((const unsigned*)((const char*)(gbase) + (voff)[_i]), (LAS unsigned*)(lds + (bufoff) + ldsw + _i * 8192), 16, 0, 0); } while (0)
; #define PG8_LDA(dst, b, h) do { _Pragma("unroll") for (int m = 0; m < 4; ++m) _Pragma("unroll") for (int k = 0; k < 2; ++k) dst[m][k] = *(const LAS bf16x8*)(lds + PG8_SA(b, h) + aoff + m * 2048 + k * 1024); } while (0)
; #define PG8_LDB(dst, b, h) do { _Pragma("unroll") for (int n = 0; n < 2; ++n) _Pragma("unroll") for (int k = 0; k < 2; ++k) dst[n][k] = *(const LAS bf16x8*)(lds + PG8_SB(b, h) + boff + n * 2048 + k * 1024); } while (0)
; #define PG8_WAIT_V(n) asm volatile("s_waitcnt vmcnt(" #n ")" ::: "memory")
; template <class Epi>
; __device__ __forceinline__ void gemm_phase(LAS unsigned char* lds, const Gemm g, const StaticOrder& S, const Epi& E) {
;     ...
;             PG8_LDB(B1, 1, 1); PG8_STAGE(PG8_SB(1, 0), b3, voffB);
;             PG8_BAR; PG8_WAIT_L(0); PG8_MMA(0, 1, At, B1); PG8_BAR;
;             PG8_LDA(At, 1, 1); PG8_STAGE(PG8_SA(1, 0), a3, voffA);
;             PG8_BAR; PG8_WAIT_L(0); PG8_MMA(1, 0, At, B0); PG8_BAR; PG8_SCHED;
;             PG8_STAGE(PG8_SB(1, 1), b3 + hstepB, voffB);
;             PG8_WAIT_V(6); PG8_BAR; PG8_MMA(1, 1, At, B1); PG8_BAR;
;     __device__ __forceinline__ void operator()(AccRef acc, const Unit& u, int wr, int wc, int fr, int fq) const {
;     ...
;         { const float* cv = cw + 128 * u.pn + clb; const float* cg = cv + FH; const float* bp = cb + 128 * u.pn + clb;
;           cwv[0][0] = *(const f32x4*)(cv); cwv[0][1] = *(const f32x4*)(cv + F2); cwv[0][2] = *(const f32x4*)(cv + 2 * F2); cwv[0][3] = *(const f32x4*)(bp);
;           cwv[0][4] = *(const f32x4*)(cg); cwv[0][5] = *(const f32x4*)(cg + F2); cwv[0][6] = *(const f32x4*)(cg + 2 * F2); cwv[0][7] = *(const f32x4*)(bp + FH); }
;         if (fr == 15) {
; #pragma unroll
;             for (int ai = 0; ai < 2; ++ai)
; #pragma unroll
;                 for (int bj = 0; bj < 2; ++bj)
; #pragma unroll
;                     for (int n = 0; n < 2; ++n) { *(LAS f32x4*)(xch + ((ai * 2 + wr) * 2 + 0) * 256 + bj * 128 + clb + 4 * n) = acc[ai][bj][2][n]; *(LAS f32x4*)(xch + ((ai * 2 + wr) * 2 + 1) * 256 + bj * 128 + clb + 4 * n) = acc[ai][bj][3][n]; }
	s_nop 1
	ds_read_b128 v[112:115], v244 offset:49152
	ds_read_b128 v[116:119], v244 offset:50176
	ds_read_b128 v[120:123], v244 offset:51200
	ds_read_b128 v[124:127], v244 offset:52224
	ds_read_b128 v[160:163], v244 offset:53248
	ds_read_b128 v[164:167], v244 offset:54272
	ds_read_b128 v[168:171], v244 offset:55296
	ds_read_b128 v[172:175], v244 offset:56320
	s_add_i32 s36, s80, s6
	v_lshl_add_u64 v[254:255], v[196:197], 0, s[14:15]
	s_mov_b32 m0, s36
	s_nop 0
	global_load_lds_dwordx4 v[254:255], off
	v_lshl_add_u64 v[254:255], v[198:199], 0, s[14:15]
	s_add_i32 m0, s36, 0x2000
	s_nop 0
	global_load_lds_dwordx4 v[254:255], off
	s_mov_b32 m0, s68
	v_lshl_add_u64 v[254:255], v[200:201], 0, s[14:15]
	global_load_lds_dwordx4 v[254:255], off
	v_lshl_add_u64 v[254:255], v[202:203], 0, s[14:15]
	s_mov_b32 m0, s69
	s_nop 0
	global_load_lds_dwordx4 v[254:255], off
	s_add_u32 s36, s40, 0x40080
	s_addc_u32 s37, s41, 0
	s_add_i32 s40, s42, s6
	v_lshl_add_u64 v[254:255], s[36:37], 0, v[214:215]
	s_mov_b32 m0, s40
	s_nop 0
	global_load_lds_dwordx4 v[254:255], off
	v_lshl_add_u64 v[254:255], s[36:37], 0, v[210:211]
	s_add_i32 m0, s40, 0x2000
	s_nop 0
	global_load_lds_dwordx4 v[254:255], off
	s_waitcnt vmcnt(6)
	s_waitcnt lgkmcnt(0)
	s_barrier
	s_setprio 1
	v_mfma_f32_16x16x32_bf16 v[92:95], v[96:99], v[112:115], v[92:95]
	v_mfma_f32_16x16x32_bf16 v[28:31], v[104:107], v[112:115], v[28:31]
	v_mfma_f32_16x16x32_bf16 v[80:83], v[96:99], v[120:123], v[80:83]
	v_mfma_f32_16x16x32_bf16 v[16:19], v[104:107], v[120:123], v[16:19]
	v_mfma_f32_16x16x32_bf16 v[76:79], v[96:99], v[160:163], v[76:79]
	v_mfma_f32_16x16x32_bf16 v[12:15], v[104:107], v[160:163], v[12:15]
	v_mfma_f32_16x16x32_bf16 v[84:87], v[96:99], v[168:171], v[84:87]
	v_mfma_f32_16x16x32_bf16 v[20:23], v[104:107], v[168:171], v[20:23]
	v_mfma_f32_16x16x32_bf16 v[92:95], v[100:103], v[116:119], v[92:95]
	v_mfma_f32_16x16x32_bf16 v[28:31], v[108:111], v[116:119], v[28:31]
	v_mfma_f32_16x16x32_bf16 v[80:83], v[100:103], v[124:127], v[80:83]
	v_mfma_f32_16x16x32_bf16 v[16:19], v[108:111], v[124:127], v[16:19]
	v_mfma_f32_16x16x32_bf16 v[76:79], v[100:103], v[164:167], v[76:79]
	v_mfma_f32_16x16x32_bf16 v[12:15], v[108:111], v[164:167], v[12:15]
	v_mfma_f32_16x16x32_bf16 v[84:87], v[100:103], v[172:175], v[84:87]
	v_mfma_f32_16x16x32_bf16 v[20:23], v[108:111], v[172:175], v[20:23]
	v_mfma_f32_16x16x32_bf16 v[88:91], v[180:183], v[112:115], v[88:91]
	v_mfma_f32_16x16x32_bf16 v[24:27], v[188:191], v[112:115], v[24:27]
	v_mfma_f32_16x16x32_bf16 v[68:71], v[180:183], v[120:123], v[68:71]
	v_mfma_f32_16x16x32_bf16 v[4:7], v[188:191], v[120:123], v[4:7]
	v_mfma_f32_16x16x32_bf16 v[64:67], v[180:183], v[160:163], v[64:67]
	v_mfma_f32_16x16x32_bf16 v[0:3], v[188:191], v[160:163], v[0:3]
	v_mfma_f32_16x16x32_bf16 v[72:75], v[180:183], v[168:171], v[72:75]
	v_mfma_f32_16x16x32_bf16 v[8:11], v[188:191], v[168:171], v[8:11]
	v_mfma_f32_16x16x32_bf16 v[88:91], v[184:187], v[116:119], v[88:91]
	v_mfma_f32_16x16x32_bf16 v[24:27], v[192:195], v[116:119], v[24:27]
	v_mfma_f32_16x16x32_bf16 v[68:71], v[184:187], v[124:127], v[68:71]
	v_mfma_f32_16x16x32_bf16 v[4:7], v[192:195], v[124:127], v[4:7]
	v_mfma_f32_16x16x32_bf16 v[64:67], v[184:187], v[164:167], v[64:67]
	v_mfma_f32_16x16x32_bf16 v[0:3], v[192:195], v[164:167], v[0:3]
	v_mfma_f32_16x16x32_bf16 v[72:75], v[184:187], v[172:175], v[72:75]
	v_mfma_f32_16x16x32_bf16 v[8:11], v[192:195], v[172:175], v[8:11]
	s_setprio 0
	s_add_i32 s79, s79, 2
	s_add_u32 s77, s77, 0x100
	s_addc_u32 s78, s78, 0
	s_cmp_gt_u32 s79, 13
	s_mov_b64 s[36:37], s[38:39]
	s_barrier
	s_cbranch_scc0 .LBB0_309
	s_lshl_b32 s36, s35, 7
	s_ashr_i32 s37, s36, 31
	s_lshl_b64 s[38:39], s[36:37], 2
	v_lshl_add_u64 v[96:97], v[220:221], 0, s[38:39]
	v_add_co_u32_e32 v100, vcc, 0x5000, v96
	v_lshl_add_u64 v[98:99], v[222:223], 0, s[38:39]
	s_nop 0
	v_addc_co_u32_e32 v101, vcc, 0, v97, vcc
	v_add_co_u32_e32 v102, vcc, 0xb000, v96
	global_load_dwordx4 v[160:163], v[96:97], off
	s_nop 0
	v_addc_co_u32_e32 v103, vcc, 0, v97, vcc
	global_load_dwordx4 v[164:167], v[100:101], off offset:2048
	global_load_dwordx4 v[168:171], v[102:103], off
	global_load_dwordx4 v[172:175], v[98:99], off
	v_add_co_u32_e32 v100, vcc, s49, v96
	s_nop 1
	v_addc_co_u32_e32 v101, vcc, 0, v97, vcc
	v_add_co_u32_e32 v102, vcc, 0x8000, v96
	s_nop 1
	v_addc_co_u32_e32 v103, vcc, 0, v97, vcc
	v_add_co_u32_e32 v96, vcc, 0xd000, v96
	global_load_dwordx4 v[176:179], v[100:101], off offset:3072
	global_load_dwordx4 v[180:183], v[102:103], off offset:1024
	v_addc_co_u32_e32 v97, vcc, 0, v97, vcc
	global_load_dwordx4 v[184:187], v[96:97], off offset:3072
	v_add_co_u32_e32 v96, vcc, 0x2000, v98
	s_nop 1
	v_addc_co_u32_e32 v97, vcc, 0, v99, vcc
	global_load_dwordx4 v[188:191], v[96:97], off offset:3072
	s_and_saveexec_b64 s[38:39], s[8:9]
	s_cbranch_execz .LBB0_312
	ds_write_b128 v237, v[136:139]
	ds_write_b128 v237, v[148:151] offset:1024
	ds_write_b128 v237, v[40:43] offset:16
	ds_write_b128 v237, v[52:55] offset:1040
	ds_write_b128 v237, v[128:131] offset:512
	ds_write_b128 v237, v[140:143] offset:1536
	ds_write_b128 v237, v[32:35] offset:528
	ds_write_b128 v237, v[44:47] offset:1552
	ds_write_b128 v237, v[76:79] offset:4096
	ds_write_b128 v237, v[84:87] offset:5120
	ds_write_b128 v237, v[12:15] offset:4112
	ds_write_b128 v237, v[20:23] offset:5136
	ds_write_b128 v237, v[64:67] offset:4608
	ds_write_b128 v237, v[72:75] offset:5632
	ds_write_b128 v237, v[0:3] offset:4624
	ds_write_b128 v237, v[8:11] offset:5648

; #define PG8_STAGE(bufoff, gbase, voff) do { _Pragma("unroll") for (int _i = 0; _i < 2; ++_i) \
;         __builtin_amdgcn_global_load_lds((const unsigned*)((const char*)(gbase) + (voff)[_i]), (LAS unsigned*)(lds + (bufoff) + ldsw + _i * 8192), 16, 0, 0); } while (0)
; #define PG8_LDA(dst, b, h) do { _Pragma("unroll") for (int m = 0; m < 4; ++m) _Pragma("unroll") for (int k = 0; k < 2; ++k) dst[m][k] = *(const LAS bf16x8*)(lds + PG8_SA(b, h) + aoff + m * 2048 + k * 1024); } while (0)
; #define PG8_LDB(dst, b, h) do { _Pragma("unroll") for (int n = 0; n < 2; ++n) _Pragma("unroll") for (int k = 0; k < 2; ++k) dst[n][k] = *(const LAS bf16x8*)(lds + PG8_SB(b, h) + boff + n * 2048 + k * 1024); } while (0)
; #define PG8_MMA(ai, bj, At, Bt) do { __builtin_amdgcn_s_setprio(1); _Pragma("unroll") for (int m = 0; m < 4; ++m) _Pragma("unroll") for (int n = 0; n < 2; ++n) _Pragma("unroll") for (int k = 0; k < 2; ++k) \
;         acc[ai][bj][m][n] = __builtin_amdgcn_mfma_f32_16x16x32_bf16(Bt[n][k], At[m][k], acc[ai][bj][m][n], 0, 0, 0); __builtin_amdgcn_s_setprio(0); } while (0)
; #define PG8_WAIT_V(n) asm volatile("s_waitcnt vmcnt(" #n ")" ::: "memory")
; #define PG8_WAIT_L(n) asm volatile("s_waitcnt lgkmcnt(" #n ")" ::: "memory")
; template <class Epi>
; __device__ __forceinline__ void gemm_phase(LAS unsigned char* lds, const Gemm g, const StaticOrder& S, const Epi& E) {
;     ...
;         for (int t = 0; t < nt; t += 2) {
;             const bool last = (t == nt - 2);
;             const char* a1 = cA + (size_t)(t + 1) * kstep;
;             const char* a2 = last ? nA : cA + (size_t)(t + 2) * kstep; const char* b2 = last ? nB : cB + (size_t)(t + 2) * kstep;
;             const char* a3 = a2 + kstep; const char* b3 = b2 + kstep;
;             PG8_LDB(B0, 0, 0); PG8_SCHED; PG8_LDA(At, 0, 0); PG8_STAGE(PG8_SA(1, 1), a1 + hstepA, voffA);
;             PG8_WAIT_L(8); PG8_BAR; PG8_WAIT_L(0); PG8_MMA(0, 0, At, B0); PG8_BAR; PG8_SCHED;
;             PG8_LDB(B1, 0, 1); PG8_STAGE(PG8_SB(0, 0), b2, voffB);
;             PG8_BAR; PG8_WAIT_L(0); PG8_MMA(0, 1, At, B1); PG8_BAR;
;             PG8_LDA(At, 0, 1); PG8_STAGE(PG8_SA(0, 0), a2, voffA);
;             PG8_BAR; PG8_WAIT_L(0); PG8_MMA(1, 0, At, B0); PG8_BAR; PG8_SCHED;
;             PG8_STAGE(PG8_SB(0, 1), b2 + hstepB, voffB);
;             PG8_WAIT_V(6); PG8_BAR; PG8_MMA(1, 1, At, B1); PG8_BAR;
.LBB0_758:
	ds_read_b128 v[96:99], v243
	ds_read_b128 v[100:103], v243 offset:1024
	ds_read_b128 v[104:107], v243 offset:2048
	ds_read_b128 v[108:111], v243 offset:3072
	s_add_u32 s44, s42, 0x100
	s_addc_u32 s45, s43, 0
	s_cmp_eq_u32 s81, 12
	s_cselect_b32 s49, s35, s45
	s_cselect_b32 s48, s77, s44
	s_cselect_b32 s47, s31, s80
	s_cselect_b32 s46, s78, s79
	v_lshl_add_u64 v[176:177], s[42:43], 0, v[224:225]
	s_add_i32 m0, s9, 0xc000
	ds_read_b128 v[112:115], v244
	ds_read_b128 v[116:119], v244 offset:1024
	ds_read_b128 v[120:123], v244 offset:2048
	ds_read_b128 v[124:127], v244 offset:3072
	ds_read_b128 v[160:163], v244 offset:4096
	ds_read_b128 v[164:167], v244 offset:5120
	ds_read_b128 v[168:171], v244 offset:6144
	ds_read_b128 v[172:175], v244 offset:7168
	global_load_lds_dwordx4 v[176:177], off
	v_lshl_add_u64 v[176:177], s[42:43], 0, v[226:227]
	s_add_i32 m0, s9, 0xe000
	s_nop 0
	global_load_lds_dwordx4 v[176:177], off
	ds_read_b128 v[176:179], v245
	ds_read_b128 v[180:183], v245 offset:1024
	ds_read_b128 v[184:187], v245 offset:2048
	ds_read_b128 v[188:191], v245 offset:3072
	s_waitcnt lgkmcnt(0)
	s_barrier
	s_setprio 1
	v_mfma_f32_16x16x32_bf16 v[156:159], v[96:99], v[112:115], v[156:159]
	v_mfma_f32_16x16x32_bf16 v[60:63], v[104:107], v[112:115], v[60:63]
	v_mfma_f32_16x16x32_bf16 v[144:147], v[96:99], v[120:123], v[144:147]
	v_mfma_f32_16x16x32_bf16 v[48:51], v[104:107], v[120:123], v[48:51]
	v_mfma_f32_16x16x32_bf16 v[136:139], v[96:99], v[160:163], v[136:139]
	v_mfma_f32_16x16x32_bf16 v[40:43], v[104:107], v[160:163], v[40:43]
	v_mfma_f32_16x16x32_bf16 v[148:151], v[96:99], v[168:171], v[148:151]
	v_mfma_f32_16x16x32_bf16 v[52:55], v[104:107], v[168:171], v[52:55]
	v_mfma_f32_16x16x32_bf16 v[156:159], v[100:103], v[116:119], v[156:159]
	v_mfma_f32_16x16x32_bf16 v[60:63], v[108:111], v[116:119], v[60:63]
	v_mfma_f32_16x16x32_bf16 v[144:147], v[100:103], v[124:127], v[144:147]
	v_mfma_f32_16x16x32_bf16 v[48:51], v[108:111], v[124:127], v[48:51]
	v_mfma_f32_16x16x32_bf16 v[136:139], v[100:103], v[164:167], v[136:139]
	v_mfma_f32_16x16x32_bf16 v[40:43], v[108:111], v[164:167], v[40:43]
	v_mfma_f32_16x16x32_bf16 v[148:151], v[100:103], v[172:175], v[148:151]
	v_mfma_f32_16x16x32_bf16 v[52:55], v[108:111], v[172:175], v[52:55]
	v_mfma_f32_16x16x32_bf16 v[152:155], v[176:179], v[112:115], v[152:155]
	v_mfma_f32_16x16x32_bf16 v[56:59], v[184:187], v[112:115], v[56:59]
	v_mfma_f32_16x16x32_bf16 v[36:39], v[184:187], v[120:123], v[36:39]
	v_mfma_f32_16x16x32_bf16 v[32:35], v[184:187], v[160:163], v[32:35]
	v_mfma_f32_16x16x32_bf16 v[44:47], v[184:187], v[168:171], v[44:47]
	v_mfma_f32_16x16x32_bf16 v[152:155], v[180:183], v[116:119], v[152:155]
	v_mfma_f32_16x16x32_bf16 v[56:59], v[188:191], v[116:119], v[56:59]
	v_mfma_f32_16x16x32_bf16 v[112:115], v[176:179], v[120:123], v[132:135]
	v_mfma_f32_16x16x32_bf16 v[36:39], v[188:191], v[124:127], v[36:39]
	v_mfma_f32_16x16x32_bf16 v[116:119], v[176:179], v[160:163], v[128:131]
	v_mfma_f32_16x16x32_bf16 v[32:35], v[188:191], v[164:167], v[32:35]
	v_mfma_f32_16x16x32_bf16 v[120:123], v[176:179], v[168:171], v[140:143]
	v_mfma_f32_16x16x32_bf16 v[44:47], v[188:191], v[172:175], v[44:47]
	v_mfma_f32_16x16x32_bf16 v[112:115], v[180:183], v[124:127], v[112:115]
	v_mfma_f32_16x16x32_bf16 v[116:119], v[180:183], v[164:167], v[116:119]
	v_mfma_f32_16x16x32_bf16 v[120:123], v[180:183], v[172:175], v[120:123]
	s_setprio 0
	s_barrier
	s_nop 1
	ds_read_b128 v[124:127], v244 offset:16384
	ds_read_b128 v[128:131], v244 offset:17408
	ds_read_b128 v[132:135], v244 offset:18432
	ds_read_b128 v[140:143], v244 offset:19456
	ds_read_b128 v[160:163], v244 offset:20480
	ds_read_b128 v[164:167], v244 offset:21504
	ds_read_b128 v[168:171], v244 offset:22528
	ds_read_b128 v[172:175], v244 offset:23552
	s_add_i32 s42, s74, s7
	v_lshl_add_u64 v[196:197], s[46:47], 0, v[214:215]
	s_mov_b32 m0, s42
	s_nop 0
	global_load_lds_dwordx4 v[196:197], off
	v_lshl_add_u64 v[198:199], s[46:47], 0, v[210:211]
	s_add_i32 m0, s42, 0x2000
	s_nop 0
	global_load_lds_dwordx4 v[198:199], off
	s_mov_b32 m0, s9
	v_lshl_add_u64 v[200:201], s[48:49], 0, v[216:217]
	global_load_lds_dwordx4 v[200:201], off
	v_lshl_add_u64 v[202:203], s[48:49], 0, v[212:213]
	s_mov_b32 m0, s63
	s_nop 0
	global_load_lds_dwordx4 v[202:203], off
	s_add_u32 s42, s46, 0x40000
	s_addc_u32 s43, s47, 0
	s_add_i32 s82, s75, s7
	v_lshl_add_u64 v[254:255], s[42:43], 0, v[214:215]
	s_mov_b32 m0, s82
	s_nop 0
	global_load_lds_dwordx4 v[254:255], off
	v_lshl_add_u64 v[254:255], s[42:43], 0, v[210:211]
	s_add_i32 m0, s82, 0x2000
	s_nop 0
	global_load_lds_dwordx4 v[254:255], off
	s_waitcnt vmcnt(6)
	s_waitcnt lgkmcnt(0)
	s_barrier
; #define PG8_STAGE(bufoff, gbase, voff) do { _Pragma("unroll") for (int _i = 0; _i < 2; ++_i) \
;         __builtin_amdgcn_global_load_lds((const unsigned*)((const char*)(gbase) + (voff)[_i]), (LAS unsigned*)(lds + (bufoff) + ldsw + _i * 8192), 16, 0, 0); } while (0)
; #define PG8_LDA(dst, b, h) do { _Pragma("unroll") for (int m = 0; m < 4; ++m) _Pragma("unroll") for (int k = 0; k < 2; ++k) dst[m][k] = *(const LAS bf16x8*)(lds + PG8_SA(b, h) + aoff + m * 2048 + k * 1024); } while (0)
; #define PG8_LDB(dst, b, h) do { _Pragma("unroll") for (int n = 0; n < 2; ++n) _Pragma("unroll") for (int k = 0; k < 2; ++k) dst[n][k] = *(const LAS bf16x8*)(lds + PG8_SB(b, h) + boff + n * 2048 + k * 1024); } while (0)
; #define PG8_MMA(ai, bj, At, Bt) do { __builtin_amdgcn_s_setprio(1); _Pragma("unroll") for (int m = 0; m < 4; ++m) _Pragma("unroll") for (int n = 0; n < 2; ++n) _Pragma("unroll") for (int k = 0; k < 2; ++k) \
;         acc[ai][bj][m][n] = __builtin_amdgcn_mfma_f32_16x16x32_bf16(Bt[n][k], At[m][k], acc[ai][bj][m][n], 0, 0, 0); __builtin_amdgcn_s_setprio(0); } while (0)
; #define PG8_WAIT_V(n) asm volatile("s_waitcnt vmcnt(" #n ")" ::: "memory")
; #define PG8_WAIT_L(n) asm volatile("s_waitcnt lgkmcnt(" #n ")" ::: "memory")
; #define PG8_BAR __builtin_amdgcn_s_barrier()
; #define PG8_SCHED __builtin_amdgcn_sched_barrier(0)
; template <class Epi>
; __device__ __forceinline__ void gemm_phase(LAS unsigned char* lds, const Gemm g, const StaticOrder& S, const Epi& E) {
;     ...
;             PG8_BAR; PG8_WAIT_L(0); PG8_MMA(1, 0, At, B0); PG8_BAR; PG8_SCHED;
;             PG8_STAGE(PG8_SB(0, 1), b2 + hstepB, voffB);
;             PG8_WAIT_V(6); PG8_BAR; PG8_MMA(1, 1, At, B1); PG8_BAR;
;             PG8_LDB(B0, 1, 0); PG8_SCHED; PG8_LDA(At, 1, 0); PG8_STAGE(PG8_SA(0, 1), a2 + hstepA, voffA);
;             PG8_WAIT_L(8); PG8_BAR; PG8_WAIT_L(0); PG8_MMA(0, 0, At, B0); PG8_BAR; PG8_SCHED;
;             PG8_LDB(B1, 1, 1); PG8_STAGE(PG8_SB(1, 0), b3, voffB);
;             PG8_BAR; PG8_WAIT_L(0); PG8_MMA(0, 1, At, B1); PG8_BAR;
	s_setprio 1
	v_mfma_f32_16x16x32_bf16 v[92:95], v[96:99], v[124:127], v[92:95]
	v_mfma_f32_16x16x32_bf16 v[28:31], v[104:107], v[124:127], v[28:31]
	v_mfma_f32_16x16x32_bf16 v[80:83], v[96:99], v[132:135], v[80:83]
	v_mfma_f32_16x16x32_bf16 v[16:19], v[104:107], v[132:135], v[16:19]
	v_mfma_f32_16x16x32_bf16 v[76:79], v[96:99], v[160:163], v[76:79]
	v_mfma_f32_16x16x32_bf16 v[12:15], v[104:107], v[160:163], v[12:15]
	v_mfma_f32_16x16x32_bf16 v[84:87], v[96:99], v[168:171], v[84:87]
	v_mfma_f32_16x16x32_bf16 v[20:23], v[104:107], v[168:171], v[20:23]
	v_mfma_f32_16x16x32_bf16 v[92:95], v[100:103], v[128:131], v[92:95]
	v_mfma_f32_16x16x32_bf16 v[28:31], v[108:111], v[128:131], v[28:31]
	v_mfma_f32_16x16x32_bf16 v[80:83], v[100:103], v[140:143], v[80:83]
	v_mfma_f32_16x16x32_bf16 v[16:19], v[108:111], v[140:143], v[16:19]
	v_mfma_f32_16x16x32_bf16 v[76:79], v[100:103], v[164:167], v[76:79]
	v_mfma_f32_16x16x32_bf16 v[12:15], v[108:111], v[164:167], v[12:15]
	v_mfma_f32_16x16x32_bf16 v[84:87], v[100:103], v[172:175], v[84:87]
	v_mfma_f32_16x16x32_bf16 v[20:23], v[108:111], v[172:175], v[20:23]
	v_mfma_f32_16x16x32_bf16 v[88:91], v[176:179], v[124:127], v[88:91]
	v_mfma_f32_16x16x32_bf16 v[24:27], v[184:187], v[124:127], v[24:27]
	v_mfma_f32_16x16x32_bf16 v[68:71], v[176:179], v[132:135], v[68:71]
	v_mfma_f32_16x16x32_bf16 v[4:7], v[184:187], v[132:135], v[4:7]
	v_mfma_f32_16x16x32_bf16 v[64:67], v[176:179], v[160:163], v[64:67]
	v_mfma_f32_16x16x32_bf16 v[0:3], v[184:187], v[160:163], v[0:3]
	v_mfma_f32_16x16x32_bf16 v[72:75], v[176:179], v[168:171], v[72:75]
	v_mfma_f32_16x16x32_bf16 v[8:11], v[184:187], v[168:171], v[8:11]
	v_mfma_f32_16x16x32_bf16 v[88:91], v[180:183], v[128:131], v[88:91]
	v_mfma_f32_16x16x32_bf16 v[24:27], v[188:191], v[128:131], v[24:27]
	v_mfma_f32_16x16x32_bf16 v[68:71], v[180:183], v[140:143], v[68:71]
	v_mfma_f32_16x16x32_bf16 v[4:7], v[188:191], v[140:143], v[4:7]
	v_mfma_f32_16x16x32_bf16 v[64:67], v[180:183], v[164:167], v[64:67]
	v_mfma_f32_16x16x32_bf16 v[0:3], v[188:191], v[164:167], v[0:3]
	v_mfma_f32_16x16x32_bf16 v[72:75], v[180:183], v[172:175], v[72:75]
	v_mfma_f32_16x16x32_bf16 v[8:11], v[188:191], v[172:175], v[8:11]
	s_setprio 0
	s_add_i32 s82, 0, 0x18000
	v_add_u32_e32 v108, s82, v235
	s_barrier
	ds_read_b128 v[96:99], v108
	ds_read_b128 v[100:103], v108 offset:1024
	ds_read_b128 v[104:107], v108 offset:2048
	ds_read_b128 v[108:111], v108 offset:3072
	s_add_u32 s42, s48, 0x40000
	s_addc_u32 s43, s49, 0
	s_mov_b32 m0, s68
	v_lshl_add_u64 v[132:133], s[42:43], 0, v[216:217]
	ds_read_b128 v[124:127], v244 offset:32768
	ds_read_b128 v[128:131], v244 offset:33792
	ds_read_b128 v[140:143], v244 offset:34816
	ds_read_b128 v[160:163], v244 offset:35840
	ds_read_b128 v[164:167], v244 offset:36864
	ds_read_b128 v[168:171], v244 offset:37888
	ds_read_b128 v[172:175], v244 offset:38912
	ds_read_b128 v[176:179], v244 offset:39936
	global_load_lds_dwordx4 v[132:133], off
	v_lshl_add_u64 v[132:133], s[42:43], 0, v[212:213]
	s_mov_b32 m0, s69
	s_nop 0
	global_load_lds_dwordx4 v[132:133], off
	s_add_i32 s48, 0, 0x1c000
	v_add_u32_e32 v132, s48, v235
	ds_read_b128 v[180:183], v132
	ds_read_b128 v[184:187], v132 offset:1024
	ds_read_b128 v[188:191], v132 offset:2048
	ds_read_b128 v[192:195], v132 offset:3072
	s_waitcnt lgkmcnt(0)
	s_barrier
	s_setprio 1
	v_mfma_f32_16x16x32_bf16 v[132:135], v[96:99], v[124:127], v[156:159]
	v_mfma_f32_16x16x32_bf16 v[156:159], v[100:103], v[128:131], v[132:135]
	v_mfma_f32_16x16x32_bf16 v[132:135], v[96:99], v[140:143], v[144:147]
	v_mfma_f32_16x16x32_bf16 v[144:147], v[100:103], v[160:163], v[132:135]
	v_mfma_f32_16x16x32_bf16 v[132:135], v[96:99], v[164:167], v[136:139]
	v_mfma_f32_16x16x32_bf16 v[60:63], v[104:107], v[124:127], v[60:63]
	v_mfma_f32_16x16x32_bf16 v[48:51], v[104:107], v[140:143], v[48:51]
	v_mfma_f32_16x16x32_bf16 v[136:139], v[100:103], v[168:171], v[132:135]
	v_mfma_f32_16x16x32_bf16 v[40:43], v[104:107], v[164:167], v[40:43]
	v_mfma_f32_16x16x32_bf16 v[132:135], v[96:99], v[172:175], v[148:151]
	v_mfma_f32_16x16x32_bf16 v[52:55], v[104:107], v[172:175], v[52:55]
	v_mfma_f32_16x16x32_bf16 v[60:63], v[108:111], v[128:131], v[60:63]
	v_mfma_f32_16x16x32_bf16 v[48:51], v[108:111], v[160:163], v[48:51]
	v_mfma_f32_16x16x32_bf16 v[40:43], v[108:111], v[168:171], v[40:43]
	v_mfma_f32_16x16x32_bf16 v[148:151], v[100:103], v[176:179], v[132:135]
	v_mfma_f32_16x16x32_bf16 v[52:55], v[108:111], v[176:179], v[52:55]
	v_mfma_f32_16x16x32_bf16 v[132:135], v[180:183], v[124:127], v[152:155]
	v_mfma_f32_16x16x32_bf16 v[112:115], v[180:183], v[140:143], v[112:115]
	v_mfma_f32_16x16x32_bf16 v[152:155], v[184:187], v[128:131], v[132:135]
	v_mfma_f32_16x16x32_bf16 v[56:59], v[188:191], v[124:127], v[56:59]
	v_mfma_f32_16x16x32_bf16 v[132:135], v[184:187], v[160:163], v[112:115]
	v_mfma_f32_16x16x32_bf16 v[112:115], v[180:183], v[164:167], v[116:119]
	v_mfma_f32_16x16x32_bf16 v[56:59], v[192:195], v[128:131], v[56:59]
	v_mfma_f32_16x16x32_bf16 v[36:39], v[188:191], v[140:143], v[36:39]
	v_mfma_f32_16x16x32_bf16 v[128:131], v[184:187], v[168:171], v[112:115]
	v_mfma_f32_16x16x32_bf16 v[32:35], v[188:191], v[164:167], v[32:35]
	v_mfma_f32_16x16x32_bf16 v[112:115], v[180:183], v[172:175], v[120:123]
	v_mfma_f32_16x16x32_bf16 v[44:47], v[188:191], v[172:175], v[44:47]
	v_mfma_f32_16x16x32_bf16 v[36:39], v[192:195], v[160:163], v[36:39]
	v_mfma_f32_16x16x32_bf16 v[32:35], v[192:195], v[168:171], v[32:35]
	v_mfma_f32_16x16x32_bf16 v[140:143], v[184:187], v[176:179], v[112:115]
	v_mfma_f32_16x16x32_bf16 v[44:47], v[192:195], v[176:179], v[44:47]
	s_setprio 0
	s_barrier
; #define LAS __attribute__((address_space(3)))
; #define PG8_STAGE(bufoff, gbase, voff) do { _Pragma("unroll") for (int _i = 0; _i < 2; ++_i) \
;         __builtin_amdgcn_global_load_lds((const unsigned*)((const char*)(gbase) + (voff)[_i]), (LAS unsigned*)(lds + (bufoff) + ldsw + _i * 8192), 16, 0, 0); } while (0)
; #define PG8_LDA(dst, b, h) do { _Pragma("unroll") for (int m = 0; m < 4; ++m) _Pragma("unroll") for (int k = 0; k < 2; ++k) dst[m][k] = *(const LAS bf16x8*)(lds + PG8_SA(b, h) + aoff + m * 2048 + k * 1024); } while (0)
; #define PG8_LDB(dst, b, h) do { _Pragma("unroll") for (int n = 0; n < 2; ++n) _Pragma("unroll") for (int k = 0; k < 2; ++k) dst[n][k] = *(const LAS bf16x8*)(lds + PG8_SB(b, h) + boff + n * 2048 + k * 1024); } while (0)
; #define PG8_WAIT_V(n) asm volatile("s_waitcnt vmcnt(" #n ")" ::: "memory")
; template <class Epi>
; __device__ __forceinline__ void gemm_phase(LAS unsigned char* lds, const Gemm g, const StaticOrder& S, const Epi& E) {
;     ...
;             PG8_LDB(B1, 1, 1); PG8_STAGE(PG8_SB(1, 0), b3, voffB);
;             PG8_BAR; PG8_WAIT_L(0); PG8_MMA(0, 1, At, B1); PG8_BAR;
;             PG8_LDA(At, 1, 1); PG8_STAGE(PG8_SA(1, 0), a3, voffA);
;             PG8_BAR; PG8_WAIT_L(0); PG8_MMA(1, 0, At, B0); PG8_BAR; PG8_SCHED;
;             PG8_STAGE(PG8_SB(1, 1), b3 + hstepB, voffB);
;             PG8_WAIT_V(6); PG8_BAR; PG8_MMA(1, 1, At, B1); PG8_BAR;
;     __device__ __forceinline__ void operator()(AccRef acc, const Unit& u, int wr, int wc, int fr, int fq) const {
;     ...
;         { const float* cv = cw + 128 * u.pn + clb; const float* cg = cv + FH; const float* bp = cb + 128 * u.pn + clb;
;           cwv[0][0] = *(const f32x4*)(cv); cwv[0][1] = *(const f32x4*)(cv + F2); cwv[0][2] = *(const f32x4*)(cv + 2 * F2); cwv[0][3] = *(const f32x4*)(bp);
;           cwv[0][4] = *(const f32x4*)(cg); cwv[0][5] = *(const f32x4*)(cg + F2); cwv[0][6] = *(const f32x4*)(cg + 2 * F2); cwv[0][7] = *(const f32x4*)(bp + FH); }
;         if (fr == 15) {
; #pragma unroll
;             for (int ai = 0; ai < 2; ++ai)
; #pragma unroll
;                 for (int bj = 0; bj < 2; ++bj)
; #pragma unroll
;                     for (int n = 0; n < 2; ++n) { *(LAS f32x4*)(xch + ((ai * 2 + wr) * 2 + 0) * 256 + bj * 128 + clb + 4 * n) = acc[ai][bj][2][n]; *(LAS f32x4*)(xch + ((ai * 2 + wr) * 2 + 1) * 256 + bj * 128 + clb + 4 * n) = acc[ai][bj][3][n]; }
	s_nop 1
	ds_read_b128 v[112:115], v244 offset:49152
	ds_read_b128 v[116:119], v244 offset:50176
	ds_read_b128 v[120:123], v244 offset:51200
	ds_read_b128 v[124:127], v244 offset:52224
	ds_read_b128 v[160:163], v244 offset:53248
	ds_read_b128 v[164:167], v244 offset:54272
	ds_read_b128 v[168:171], v244 offset:55296
	ds_read_b128 v[172:175], v244 offset:56320
	s_add_i32 s42, s82, s7
	v_lshl_add_u64 v[254:255], v[196:197], 0, s[20:21]
	s_mov_b32 m0, s42
	s_nop 0
	global_load_lds_dwordx4 v[254:255], off
	v_lshl_add_u64 v[254:255], v[198:199], 0, s[20:21]
	s_add_i32 m0, s42, 0x2000
	s_nop 0
	global_load_lds_dwordx4 v[254:255], off
	s_mov_b32 m0, s72
	v_lshl_add_u64 v[254:255], v[200:201], 0, s[20:21]
	global_load_lds_dwordx4 v[254:255], off
	v_lshl_add_u64 v[254:255], v[202:203], 0, s[20:21]
	s_mov_b32 m0, s73
	s_nop 0
	global_load_lds_dwordx4 v[254:255], off
	s_add_u32 s42, s46, 0x40080
	s_addc_u32 s43, s47, 0
	s_add_i32 s46, s48, s7
	v_lshl_add_u64 v[254:255], s[42:43], 0, v[214:215]
	s_mov_b32 m0, s46
	s_nop 0
	global_load_lds_dwordx4 v[254:255], off
	v_lshl_add_u64 v[254:255], s[42:43], 0, v[210:211]
	s_add_i32 m0, s46, 0x2000
	s_nop 0
	global_load_lds_dwordx4 v[254:255], off
	s_waitcnt vmcnt(6)
	s_waitcnt lgkmcnt(0)
	s_barrier
	s_setprio 1
	v_mfma_f32_16x16x32_bf16 v[92:95], v[96:99], v[112:115], v[92:95]
	v_mfma_f32_16x16x32_bf16 v[28:31], v[104:107], v[112:115], v[28:31]
	v_mfma_f32_16x16x32_bf16 v[80:83], v[96:99], v[120:123], v[80:83]
	v_mfma_f32_16x16x32_bf16 v[16:19], v[104:107], v[120:123], v[16:19]
	v_mfma_f32_16x16x32_bf16 v[76:79], v[96:99], v[160:163], v[76:79]
	v_mfma_f32_16x16x32_bf16 v[12:15], v[104:107], v[160:163], v[12:15]
	v_mfma_f32_16x16x32_bf16 v[84:87], v[96:99], v[168:171], v[84:87]
	v_mfma_f32_16x16x32_bf16 v[20:23], v[104:107], v[168:171], v[20:23]
	v_mfma_f32_16x16x32_bf16 v[92:95], v[100:103], v[116:119], v[92:95]
	v_mfma_f32_16x16x32_bf16 v[28:31], v[108:111], v[116:119], v[28:31]
	v_mfma_f32_16x16x32_bf16 v[80:83], v[100:103], v[124:127], v[80:83]
	v_mfma_f32_16x16x32_bf16 v[16:19], v[108:111], v[124:127], v[16:19]
	v_mfma_f32_16x16x32_bf16 v[76:79], v[100:103], v[164:167], v[76:79]
	v_mfma_f32_16x16x32_bf16 v[12:15], v[108:111], v[164:167], v[12:15]
	v_mfma_f32_16x16x32_bf16 v[84:87], v[100:103], v[172:175], v[84:87]
	v_mfma_f32_16x16x32_bf16 v[20:23], v[108:111], v[172:175], v[20:23]
	v_mfma_f32_16x16x32_bf16 v[88:91], v[180:183], v[112:115], v[88:91]
	v_mfma_f32_16x16x32_bf16 v[24:27], v[188:191], v[112:115], v[24:27]
	v_mfma_f32_16x16x32_bf16 v[68:71], v[180:183], v[120:123], v[68:71]
	v_mfma_f32_16x16x32_bf16 v[4:7], v[188:191], v[120:123], v[4:7]
	v_mfma_f32_16x16x32_bf16 v[64:67], v[180:183], v[160:163], v[64:67]
	v_mfma_f32_16x16x32_bf16 v[0:3], v[188:191], v[160:163], v[0:3]
	v_mfma_f32_16x16x32_bf16 v[72:75], v[180:183], v[168:171], v[72:75]
	v_mfma_f32_16x16x32_bf16 v[8:11], v[188:191], v[168:171], v[8:11]
	v_mfma_f32_16x16x32_bf16 v[88:91], v[184:187], v[116:119], v[88:91]
	v_mfma_f32_16x16x32_bf16 v[24:27], v[192:195], v[116:119], v[24:27]
	v_mfma_f32_16x16x32_bf16 v[68:71], v[184:187], v[124:127], v[68:71]
	v_mfma_f32_16x16x32_bf16 v[4:7], v[192:195], v[124:127], v[4:7]
	v_mfma_f32_16x16x32_bf16 v[64:67], v[184:187], v[164:167], v[64:67]
	v_mfma_f32_16x16x32_bf16 v[0:3], v[192:195], v[164:167], v[0:3]
	v_mfma_f32_16x16x32_bf16 v[72:75], v[184:187], v[172:175], v[72:75]
	v_mfma_f32_16x16x32_bf16 v[8:11], v[192:195], v[172:175], v[8:11]
	s_setprio 0
	s_add_i32 s81, s81, 2
	s_add_u32 s79, s79, 0x100
	s_addc_u32 s80, s80, 0
	s_cmp_gt_u32 s81, 13
	s_mov_b64 s[42:43], s[44:45]
	s_barrier
	s_cbranch_scc0 .LBB0_758
	s_lshl_b32 s42, s41, 7
	s_ashr_i32 s43, s42, 31
	s_lshl_b64 s[44:45], s[42:43], 2
	v_lshl_add_u64 v[96:97], v[220:221], 0, s[44:45]
	v_add_co_u32_e32 v100, vcc, 0x5000, v96
	v_lshl_add_u64 v[98:99], v[222:223], 0, s[44:45]
	s_nop 0
	v_addc_co_u32_e32 v101, vcc, 0, v97, vcc
	v_add_co_u32_e32 v102, vcc, 0xb000, v96
	global_load_dwordx4 v[160:163], v[96:97], off
	s_nop 0
	v_addc_co_u32_e32 v103, vcc, 0, v97, vcc
	global_load_dwordx4 v[164:167], v[100:101], off offset:2048
	global_load_dwordx4 v[168:171], v[102:103], off
	global_load_dwordx4 v[172:175], v[98:99], off
	v_add_co_u32_e32 v100, vcc, s70, v96
	s_nop 1
	v_addc_co_u32_e32 v101, vcc, 0, v97, vcc
	v_add_co_u32_e32 v102, vcc, 0x8000, v96
	s_nop 1
	v_addc_co_u32_e32 v103, vcc, 0, v97, vcc
	v_add_co_u32_e32 v96, vcc, 0xd000, v96
	global_load_dwordx4 v[176:179], v[100:101], off offset:3072
	global_load_dwordx4 v[180:183], v[102:103], off offset:1024
	v_addc_co_u32_e32 v97, vcc, 0, v97, vcc
	global_load_dwordx4 v[184:187], v[96:97], off offset:3072
	v_add_co_u32_e32 v96, vcc, 0x2000, v98
	s_nop 1
	v_addc_co_u32_e32 v97, vcc, 0, v99, vcc
	global_load_dwordx4 v[188:191], v[96:97], off offset:3072
	s_and_saveexec_b64 s[44:45], s[10:11]
	s_cbranch_execz .LBB0_761
	ds_write_b128 v237, v[136:139]
	ds_write_b128 v237, v[148:151] offset:1024
	ds_write_b128 v237, v[40:43] offset:16
	ds_write_b128 v237, v[52:55] offset:1040
	ds_write_b128 v237, v[128:131] offset:512
	ds_write_b128 v237, v[140:143] offset:1536
	ds_write_b128 v237, v[32:35] offset:528
	ds_write_b128 v237, v[44:47] offset:1552
	ds_write_b128 v237, v[76:79] offset:4096
	ds_write_b128 v237, v[84:87] offset:5120
	ds_write_b128 v237, v[12:15] offset:4112
	ds_write_b128 v237, v[20:23] offset:5136
	ds_write_b128 v237, v[64:67] offset:4608
	ds_write_b128 v237, v[72:75] offset:5632
	ds_write_b128 v237, v[0:3] offset:4624
	ds_write_b128 v237, v[8:11] offset:5648

; #define PG8_STAGE(bufoff, gbase, voff) do { _Pragma("unroll") for (int _i = 0; _i < 2; ++_i) \
;         __builtin_amdgcn_global_load_lds((const unsigned*)((const char*)(gbase) + (voff)[_i]), (LAS unsigned*)(lds + (bufoff) + ldsw + _i * 8192), 16, 0, 0); } while (0)
; #define PG8_LDA(dst, b, h) do { _Pragma("unroll") for (int m = 0; m < 4; ++m) _Pragma("unroll") for (int k = 0; k < 2; ++k) dst[m][k] = *(const LAS bf16x8*)(lds + PG8_SA(b, h) + aoff + m * 2048 + k * 1024); } while (0)
; #define PG8_LDB(dst, b, h) do { _Pragma("unroll") for (int n = 0; n < 2; ++n) _Pragma("unroll") for (int k = 0; k < 2; ++k) dst[n][k] = *(const LAS bf16x8*)(lds + PG8_SB(b, h) + boff + n * 2048 + k * 1024); } while (0)
; #define PG8_MMA(ai, bj, At, Bt) do { __builtin_amdgcn_s_setprio(1); _Pragma("unroll") for (int m = 0; m < 4; ++m) _Pragma("unroll") for (int n = 0; n < 2; ++n) _Pragma("unroll") for (int k = 0; k < 2; ++k) \
;         acc[ai][bj][m][n] = __builtin_amdgcn_mfma_f32_16x16x32_bf16(Bt[n][k], At[m][k], acc[ai][bj][m][n], 0, 0, 0); __builtin_amdgcn_s_setprio(0); } while (0)
; #define PG8_WAIT_V(n) asm volatile("s_waitcnt vmcnt(" #n ")" ::: "memory")
; #define PG8_WAIT_L(n) asm volatile("s_waitcnt lgkmcnt(" #n ")" ::: "memory")
; template <class Epi>
; __device__ __forceinline__ void gemm_phase(LAS unsigned char* lds, const Gemm g, const StaticOrder& S, const Epi& E) {
;     ...
;         for (int t = 0; t < nt; t += 2) {
;             const bool last = (t == nt - 2);
;             const char* a1 = cA + (size_t)(t + 1) * kstep;
;             const char* a2 = last ? nA : cA + (size_t)(t + 2) * kstep; const char* b2 = last ? nB : cB + (size_t)(t + 2) * kstep;
;             const char* a3 = a2 + kstep; const char* b3 = b2 + kstep;
;             PG8_LDB(B0, 0, 0); PG8_SCHED; PG8_LDA(At, 0, 0); PG8_STAGE(PG8_SA(1, 1), a1 + hstepA, voffA);
;             PG8_WAIT_L(8); PG8_BAR; PG8_WAIT_L(0); PG8_MMA(0, 0, At, B0); PG8_BAR; PG8_SCHED;
;             PG8_LDB(B1, 0, 1); PG8_STAGE(PG8_SB(0, 0), b2, voffB);
;             PG8_BAR; PG8_WAIT_L(0); PG8_MMA(0, 1, At, B1); PG8_BAR;
;             PG8_LDA(At, 0, 1); PG8_STAGE(PG8_SA(0, 0), a2, voffA);
;             PG8_BAR; PG8_WAIT_L(0); PG8_MMA(1, 0, At, B0); PG8_BAR; PG8_SCHED;
;             PG8_STAGE(PG8_SB(0, 1), b2 + hstepB, voffB);
;             PG8_WAIT_V(6); PG8_BAR; PG8_MMA(1, 1, At, B1); PG8_BAR;
.LBB0_1359:
	ds_read_b128 v[96:99], v243
	ds_read_b128 v[100:103], v243 offset:1024
	ds_read_b128 v[104:107], v243 offset:2048
	ds_read_b128 v[108:111], v243 offset:3072
	s_add_u32 s46, s44, 0x100
	s_addc_u32 s47, s45, 0
	s_cmp_eq_u32 s87, 12
	s_cselect_b32 s73, s37, s47
	s_cselect_b32 s72, s83, s46
	s_cselect_b32 s49, s35, s86
	s_cselect_b32 s48, s84, s85
	v_lshl_add_u64 v[176:177], s[44:45], 0, v[224:225]
	s_add_i32 m0, s9, 0xc000
	ds_read_b128 v[112:115], v244
	ds_read_b128 v[116:119], v244 offset:1024
	ds_read_b128 v[120:123], v244 offset:2048
	ds_read_b128 v[124:127], v244 offset:3072
	ds_read_b128 v[160:163], v244 offset:4096
	ds_read_b128 v[164:167], v244 offset:5120
	ds_read_b128 v[168:171], v244 offset:6144
	ds_read_b128 v[172:175], v244 offset:7168
	global_load_lds_dwordx4 v[176:177], off
	v_lshl_add_u64 v[176:177], s[44:45], 0, v[226:227]
	s_add_i32 m0, s9, 0xe000
	s_nop 0
	global_load_lds_dwordx4 v[176:177], off
	ds_read_b128 v[176:179], v245
	ds_read_b128 v[180:183], v245 offset:1024
	ds_read_b128 v[184:187], v245 offset:2048
	ds_read_b128 v[188:191], v245 offset:3072
	s_waitcnt lgkmcnt(0)
	s_barrier
	s_setprio 1
	v_mfma_f32_16x16x32_bf16 v[156:159], v[96:99], v[112:115], v[156:159]
	v_mfma_f32_16x16x32_bf16 v[60:63], v[104:107], v[112:115], v[60:63]
	v_mfma_f32_16x16x32_bf16 v[144:147], v[96:99], v[120:123], v[144:147]
	v_mfma_f32_16x16x32_bf16 v[48:51], v[104:107], v[120:123], v[48:51]
	v_mfma_f32_16x16x32_bf16 v[136:139], v[96:99], v[160:163], v[136:139]
	v_mfma_f32_16x16x32_bf16 v[40:43], v[104:107], v[160:163], v[40:43]
	v_mfma_f32_16x16x32_bf16 v[148:151], v[96:99], v[168:171], v[148:151]
	v_mfma_f32_16x16x32_bf16 v[52:55], v[104:107], v[168:171], v[52:55]
	v_mfma_f32_16x16x32_bf16 v[156:159], v[100:103], v[116:119], v[156:159]
	v_mfma_f32_16x16x32_bf16 v[60:63], v[108:111], v[116:119], v[60:63]
	v_mfma_f32_16x16x32_bf16 v[144:147], v[100:103], v[124:127], v[144:147]
	v_mfma_f32_16x16x32_bf16 v[48:51], v[108:111], v[124:127], v[48:51]
	v_mfma_f32_16x16x32_bf16 v[136:139], v[100:103], v[164:167], v[136:139]
	v_mfma_f32_16x16x32_bf16 v[40:43], v[108:111], v[164:167], v[40:43]
	v_mfma_f32_16x16x32_bf16 v[148:151], v[100:103], v[172:175], v[148:151]
	v_mfma_f32_16x16x32_bf16 v[52:55], v[108:111], v[172:175], v[52:55]
	v_mfma_f32_16x16x32_bf16 v[152:155], v[176:179], v[112:115], v[152:155]
	v_mfma_f32_16x16x32_bf16 v[56:59], v[184:187], v[112:115], v[56:59]
	v_mfma_f32_16x16x32_bf16 v[36:39], v[184:187], v[120:123], v[36:39]
	v_mfma_f32_16x16x32_bf16 v[32:35], v[184:187], v[160:163], v[32:35]
	v_mfma_f32_16x16x32_bf16 v[44:47], v[184:187], v[168:171], v[44:47]
	v_mfma_f32_16x16x32_bf16 v[152:155], v[180:183], v[116:119], v[152:155]
	v_mfma_f32_16x16x32_bf16 v[56:59], v[188:191], v[116:119], v[56:59]
	v_mfma_f32_16x16x32_bf16 v[112:115], v[176:179], v[120:123], v[132:135]
	v_mfma_f32_16x16x32_bf16 v[36:39], v[188:191], v[124:127], v[36:39]
	v_mfma_f32_16x16x32_bf16 v[116:119], v[176:179], v[160:163], v[128:131]
	v_mfma_f32_16x16x32_bf16 v[32:35], v[188:191], v[164:167], v[32:35]
	v_mfma_f32_16x16x32_bf16 v[120:123], v[176:179], v[168:171], v[140:143]
	v_mfma_f32_16x16x32_bf16 v[44:47], v[188:191], v[172:175], v[44:47]
	v_mfma_f32_16x16x32_bf16 v[112:115], v[180:183], v[124:127], v[112:115]
	v_mfma_f32_16x16x32_bf16 v[116:119], v[180:183], v[164:167], v[116:119]
	v_mfma_f32_16x16x32_bf16 v[120:123], v[180:183], v[172:175], v[120:123]
	s_setprio 0
	s_barrier
	s_nop 1
	ds_read_b128 v[124:127], v244 offset:16384
	ds_read_b128 v[128:131], v244 offset:17408
	ds_read_b128 v[132:135], v244 offset:18432
	ds_read_b128 v[140:143], v244 offset:19456
	ds_read_b128 v[160:163], v244 offset:20480
	ds_read_b128 v[164:167], v244 offset:21504
	ds_read_b128 v[168:171], v244 offset:22528
	ds_read_b128 v[172:175], v244 offset:23552
	s_add_i32 s44, s80, s7
	v_lshl_add_u64 v[196:197], s[48:49], 0, v[214:215]
	s_mov_b32 m0, s44
	s_nop 0
	global_load_lds_dwordx4 v[196:197], off
	v_lshl_add_u64 v[198:199], s[48:49], 0, v[210:211]
	s_add_i32 m0, s44, 0x2000
	s_nop 0
	global_load_lds_dwordx4 v[198:199], off
	s_mov_b32 m0, s9
	v_lshl_add_u64 v[200:201], s[72:73], 0, v[216:217]
	global_load_lds_dwordx4 v[200:201], off
	v_lshl_add_u64 v[202:203], s[72:73], 0, v[212:213]
	s_mov_b32 m0, s63
	s_nop 0
	global_load_lds_dwordx4 v[202:203], off
	s_add_u32 s44, s48, 0x40000
	s_addc_u32 s45, s49, 0
	s_add_i32 s88, s81, s7
	v_lshl_add_u64 v[254:255], s[44:45], 0, v[214:215]
	s_mov_b32 m0, s88
	s_nop 0
	global_load_lds_dwordx4 v[254:255], off
	v_lshl_add_u64 v[254:255], s[44:45], 0, v[210:211]
	s_add_i32 m0, s88, 0x2000
	s_nop 0
	global_load_lds_dwordx4 v[254:255], off
	s_waitcnt vmcnt(6)
	s_waitcnt lgkmcnt(0)
	s_barrier
; #define PG8_STAGE(bufoff, gbase, voff) do { _Pragma("unroll") for (int _i = 0; _i < 2; ++_i) \
;         __builtin_amdgcn_global_load_lds((const unsigned*)((const char*)(gbase) + (voff)[_i]), (LAS unsigned*)(lds + (bufoff) + ldsw + _i * 8192), 16, 0, 0); } while (0)
; #define PG8_LDA(dst, b, h) do { _Pragma("unroll") for (int m = 0; m < 4; ++m) _Pragma("unroll") for (int k = 0; k < 2; ++k) dst[m][k] = *(const LAS bf16x8*)(lds + PG8_SA(b, h) + aoff + m * 2048 + k * 1024); } while (0)
; #define PG8_LDB(dst, b, h) do { _Pragma("unroll") for (int n = 0; n < 2; ++n) _Pragma("unroll") for (int k = 0; k < 2; ++k) dst[n][k] = *(const LAS bf16x8*)(lds + PG8_SB(b, h) + boff + n * 2048 + k * 1024); } while (0)
; #define PG8_MMA(ai, bj, At, Bt) do { __builtin_amdgcn_s_setprio(1); _Pragma("unroll") for (int m = 0; m < 4; ++m) _Pragma("unroll") for (int n = 0; n < 2; ++n) _Pragma("unroll") for (int k = 0; k < 2; ++k) \
;         acc[ai][bj][m][n] = __builtin_amdgcn_mfma_f32_16x16x32_bf16(Bt[n][k], At[m][k], acc[ai][bj][m][n], 0, 0, 0); __builtin_amdgcn_s_setprio(0); } while (0)
; #define PG8_WAIT_V(n) asm volatile("s_waitcnt vmcnt(" #n ")" ::: "memory")
; #define PG8_WAIT_L(n) asm volatile("s_waitcnt lgkmcnt(" #n ")" ::: "memory")
; #define PG8_BAR __builtin_amdgcn_s_barrier()
; #define PG8_SCHED __builtin_amdgcn_sched_barrier(0)
; template <class Epi>
; __device__ __forceinline__ void gemm_phase(LAS unsigned char* lds, const Gemm g, const StaticOrder& S, const Epi& E) {
;     ...
;             PG8_BAR; PG8_WAIT_L(0); PG8_MMA(1, 0, At, B0); PG8_BAR; PG8_SCHED;
;             PG8_STAGE(PG8_SB(0, 1), b2 + hstepB, voffB);
;             PG8_WAIT_V(6); PG8_BAR; PG8_MMA(1, 1, At, B1); PG8_BAR;
;             PG8_LDB(B0, 1, 0); PG8_SCHED; PG8_LDA(At, 1, 0); PG8_STAGE(PG8_SA(0, 1), a2 + hstepA, voffA);
;             PG8_WAIT_L(8); PG8_BAR; PG8_WAIT_L(0); PG8_MMA(0, 0, At, B0); PG8_BAR; PG8_SCHED;
;             PG8_LDB(B1, 1, 1); PG8_STAGE(PG8_SB(1, 0), b3, voffB);
;             PG8_BAR; PG8_WAIT_L(0); PG8_MMA(0, 1, At, B1); PG8_BAR;
	s_setprio 1
	v_mfma_f32_16x16x32_bf16 v[92:95], v[96:99], v[124:127], v[92:95]
	v_mfma_f32_16x16x32_bf16 v[28:31], v[104:107], v[124:127], v[28:31]
	v_mfma_f32_16x16x32_bf16 v[80:83], v[96:99], v[132:135], v[80:83]
	v_mfma_f32_16x16x32_bf16 v[16:19], v[104:107], v[132:135], v[16:19]
	v_mfma_f32_16x16x32_bf16 v[76:79], v[96:99], v[160:163], v[76:79]
	v_mfma_f32_16x16x32_bf16 v[12:15], v[104:107], v[160:163], v[12:15]
	v_mfma_f32_16x16x32_bf16 v[84:87], v[96:99], v[168:171], v[84:87]
	v_mfma_f32_16x16x32_bf16 v[20:23], v[104:107], v[168:171], v[20:23]
	v_mfma_f32_16x16x32_bf16 v[92:95], v[100:103], v[128:131], v[92:95]
	v_mfma_f32_16x16x32_bf16 v[28:31], v[108:111], v[128:131], v[28:31]
	v_mfma_f32_16x16x32_bf16 v[80:83], v[100:103], v[140:143], v[80:83]
	v_mfma_f32_16x16x32_bf16 v[16:19], v[108:111], v[140:143], v[16:19]
	v_mfma_f32_16x16x32_bf16 v[76:79], v[100:103], v[164:167], v[76:79]
	v_mfma_f32_16x16x32_bf16 v[12:15], v[108:111], v[164:167], v[12:15]
	v_mfma_f32_16x16x32_bf16 v[84:87], v[100:103], v[172:175], v[84:87]
	v_mfma_f32_16x16x32_bf16 v[20:23], v[108:111], v[172:175], v[20:23]
	v_mfma_f32_16x16x32_bf16 v[88:91], v[176:179], v[124:127], v[88:91]
	v_mfma_f32_16x16x32_bf16 v[24:27], v[184:187], v[124:127], v[24:27]
	v_mfma_f32_16x16x32_bf16 v[68:71], v[176:179], v[132:135], v[68:71]
	v_mfma_f32_16x16x32_bf16 v[4:7], v[184:187], v[132:135], v[4:7]
	v_mfma_f32_16x16x32_bf16 v[64:67], v[176:179], v[160:163], v[64:67]
	v_mfma_f32_16x16x32_bf16 v[0:3], v[184:187], v[160:163], v[0:3]
	v_mfma_f32_16x16x32_bf16 v[72:75], v[176:179], v[168:171], v[72:75]
	v_mfma_f32_16x16x32_bf16 v[8:11], v[184:187], v[168:171], v[8:11]
	v_mfma_f32_16x16x32_bf16 v[88:91], v[180:183], v[128:131], v[88:91]
	v_mfma_f32_16x16x32_bf16 v[24:27], v[188:191], v[128:131], v[24:27]
	v_mfma_f32_16x16x32_bf16 v[68:71], v[180:183], v[140:143], v[68:71]
	v_mfma_f32_16x16x32_bf16 v[4:7], v[188:191], v[140:143], v[4:7]
	v_mfma_f32_16x16x32_bf16 v[64:67], v[180:183], v[164:167], v[64:67]
	v_mfma_f32_16x16x32_bf16 v[0:3], v[188:191], v[164:167], v[0:3]
	v_mfma_f32_16x16x32_bf16 v[72:75], v[180:183], v[172:175], v[72:75]
	v_mfma_f32_16x16x32_bf16 v[8:11], v[188:191], v[172:175], v[8:11]
	s_setprio 0
	s_add_i32 s88, 0, 0x18000
	v_add_u32_e32 v108, s88, v235
	s_barrier
	ds_read_b128 v[96:99], v108
	ds_read_b128 v[100:103], v108 offset:1024
	ds_read_b128 v[104:107], v108 offset:2048
	ds_read_b128 v[108:111], v108 offset:3072
	s_add_u32 s44, s72, 0x40000
	s_addc_u32 s45, s73, 0
	s_mov_b32 m0, s74
	v_lshl_add_u64 v[132:133], s[44:45], 0, v[216:217]
	ds_read_b128 v[124:127], v244 offset:32768
	ds_read_b128 v[128:131], v244 offset:33792
	ds_read_b128 v[140:143], v244 offset:34816
	ds_read_b128 v[160:163], v244 offset:35840
	ds_read_b128 v[164:167], v244 offset:36864
	ds_read_b128 v[168:171], v244 offset:37888
	ds_read_b128 v[172:175], v244 offset:38912
	ds_read_b128 v[176:179], v244 offset:39936
	global_load_lds_dwordx4 v[132:133], off
	v_lshl_add_u64 v[132:133], s[44:45], 0, v[212:213]
	s_mov_b32 m0, s75
	s_nop 0
	global_load_lds_dwordx4 v[132:133], off
	s_add_i32 s72, 0, 0x1c000
	v_add_u32_e32 v132, s72, v235
	ds_read_b128 v[180:183], v132
	ds_read_b128 v[184:187], v132 offset:1024
	ds_read_b128 v[188:191], v132 offset:2048
	ds_read_b128 v[192:195], v132 offset:3072
	s_waitcnt lgkmcnt(0)
	s_barrier
	s_setprio 1
	v_mfma_f32_16x16x32_bf16 v[132:135], v[96:99], v[124:127], v[156:159]
	v_mfma_f32_16x16x32_bf16 v[156:159], v[100:103], v[128:131], v[132:135]
	v_mfma_f32_16x16x32_bf16 v[132:135], v[96:99], v[140:143], v[144:147]
	v_mfma_f32_16x16x32_bf16 v[144:147], v[100:103], v[160:163], v[132:135]
	v_mfma_f32_16x16x32_bf16 v[132:135], v[96:99], v[164:167], v[136:139]
	v_mfma_f32_16x16x32_bf16 v[60:63], v[104:107], v[124:127], v[60:63]
	v_mfma_f32_16x16x32_bf16 v[48:51], v[104:107], v[140:143], v[48:51]
	v_mfma_f32_16x16x32_bf16 v[136:139], v[100:103], v[168:171], v[132:135]
	v_mfma_f32_16x16x32_bf16 v[40:43], v[104:107], v[164:167], v[40:43]
	v_mfma_f32_16x16x32_bf16 v[132:135], v[96:99], v[172:175], v[148:151]
	v_mfma_f32_16x16x32_bf16 v[52:55], v[104:107], v[172:175], v[52:55]
	v_mfma_f32_16x16x32_bf16 v[60:63], v[108:111], v[128:131], v[60:63]
	v_mfma_f32_16x16x32_bf16 v[48:51], v[108:111], v[160:163], v[48:51]
	v_mfma_f32_16x16x32_bf16 v[40:43], v[108:111], v[168:171], v[40:43]
	v_mfma_f32_16x16x32_bf16 v[148:151], v[100:103], v[176:179], v[132:135]
	v_mfma_f32_16x16x32_bf16 v[52:55], v[108:111], v[176:179], v[52:55]
	v_mfma_f32_16x16x32_bf16 v[132:135], v[180:183], v[124:127], v[152:155]
	v_mfma_f32_16x16x32_bf16 v[112:115], v[180:183], v[140:143], v[112:115]
	v_mfma_f32_16x16x32_bf16 v[152:155], v[184:187], v[128:131], v[132:135]
	v_mfma_f32_16x16x32_bf16 v[56:59], v[188:191], v[124:127], v[56:59]
	v_mfma_f32_16x16x32_bf16 v[132:135], v[184:187], v[160:163], v[112:115]
	v_mfma_f32_16x16x32_bf16 v[112:115], v[180:183], v[164:167], v[116:119]
	v_mfma_f32_16x16x32_bf16 v[56:59], v[192:195], v[128:131], v[56:59]
	v_mfma_f32_16x16x32_bf16 v[36:39], v[188:191], v[140:143], v[36:39]
	v_mfma_f32_16x16x32_bf16 v[128:131], v[184:187], v[168:171], v[112:115]
	v_mfma_f32_16x16x32_bf16 v[32:35], v[188:191], v[164:167], v[32:35]
	v_mfma_f32_16x16x32_bf16 v[112:115], v[180:183], v[172:175], v[120:123]
	v_mfma_f32_16x16x32_bf16 v[44:47], v[188:191], v[172:175], v[44:47]
	v_mfma_f32_16x16x32_bf16 v[36:39], v[192:195], v[160:163], v[36:39]
	v_mfma_f32_16x16x32_bf16 v[32:35], v[192:195], v[168:171], v[32:35]
	v_mfma_f32_16x16x32_bf16 v[140:143], v[184:187], v[176:179], v[112:115]
	v_mfma_f32_16x16x32_bf16 v[44:47], v[192:195], v[176:179], v[44:47]
	s_setprio 0
	s_barrier
; #define LAS __attribute__((address_space(3)))
; #define PG8_STAGE(bufoff, gbase, voff) do { _Pragma("unroll") for (int _i = 0; _i < 2; ++_i) \
;         __builtin_amdgcn_global_load_lds((const unsigned*)((const char*)(gbase) + (voff)[_i]), (LAS unsigned*)(lds + (bufoff) + ldsw + _i * 8192), 16, 0, 0); } while (0)
; #define PG8_LDA(dst, b, h) do { _Pragma("unroll") for (int m = 0; m < 4; ++m) _Pragma("unroll") for (int k = 0; k < 2; ++k) dst[m][k] = *(const LAS bf16x8*)(lds + PG8_SA(b, h) + aoff + m * 2048 + k * 1024); } while (0)
; #define PG8_LDB(dst, b, h) do { _Pragma("unroll") for (int n = 0; n < 2; ++n) _Pragma("unroll") for (int k = 0; k < 2; ++k) dst[n][k] = *(const LAS bf16x8*)(lds + PG8_SB(b, h) + boff + n * 2048 + k * 1024); } while (0)
; #define PG8_WAIT_V(n) asm volatile("s_waitcnt vmcnt(" #n ")" ::: "memory")
; template <class Epi>
; __device__ __forceinline__ void gemm_phase(LAS unsigned char* lds, const Gemm g, const StaticOrder& S, const Epi& E) {
;     ...
;             PG8_LDB(B1, 1, 1); PG8_STAGE(PG8_SB(1, 0), b3, voffB);
;             PG8_BAR; PG8_WAIT_L(0); PG8_MMA(0, 1, At, B1); PG8_BAR;
;             PG8_LDA(At, 1, 1); PG8_STAGE(PG8_SA(1, 0), a3, voffA);
;             PG8_BAR; PG8_WAIT_L(0); PG8_MMA(1, 0, At, B0); PG8_BAR; PG8_SCHED;
;             PG8_STAGE(PG8_SB(1, 1), b3 + hstepB, voffB);
;             PG8_WAIT_V(6); PG8_BAR; PG8_MMA(1, 1, At, B1); PG8_BAR;
;     __device__ __forceinline__ void operator()(AccRef acc, const Unit& u, int wr, int wc, int fr, int fq) const {
;     ...
;         { const float* cv = cw + 128 * u.pn + clb; const float* cg = cv + FH; const float* bp = cb + 128 * u.pn + clb;
;           cwv[0][0] = *(const f32x4*)(cv); cwv[0][1] = *(const f32x4*)(cv + F2); cwv[0][2] = *(const f32x4*)(cv + 2 * F2); cwv[0][3] = *(const f32x4*)(bp);
;           cwv[0][4] = *(const f32x4*)(cg); cwv[0][5] = *(const f32x4*)(cg + F2); cwv[0][6] = *(const f32x4*)(cg + 2 * F2); cwv[0][7] = *(const f32x4*)(bp + FH); }
;         if (fr == 15) {
; #pragma unroll
;             for (int ai = 0; ai < 2; ++ai)
; #pragma unroll
;                 for (int bj = 0; bj < 2; ++bj)
; #pragma unroll
;                     for (int n = 0; n < 2; ++n) { *(LAS f32x4*)(xch + ((ai * 2 + wr) * 2 + 0) * 256 + bj * 128 + clb + 4 * n) = acc[ai][bj][2][n]; *(LAS f32x4*)(xch + ((ai * 2 + wr) * 2 + 1) * 256 + bj * 128 + clb + 4 * n) = acc[ai][bj][3][n]; }
	s_nop 1
	ds_read_b128 v[112:115], v244 offset:49152
	ds_read_b128 v[116:119], v244 offset:50176
	ds_read_b128 v[120:123], v244 offset:51200
	ds_read_b128 v[124:127], v244 offset:52224
	ds_read_b128 v[160:163], v244 offset:53248
	ds_read_b128 v[164:167], v244 offset:54272
	ds_read_b128 v[168:171], v244 offset:55296
	ds_read_b128 v[172:175], v244 offset:56320
	s_add_i32 s44, s88, s7
	v_lshl_add_u64 v[254:255], v[196:197], 0, s[24:25]
	s_mov_b32 m0, s44
	s_nop 0
	global_load_lds_dwordx4 v[254:255], off
	v_lshl_add_u64 v[254:255], v[198:199], 0, s[24:25]
	s_add_i32 m0, s44, 0x2000
	s_nop 0
	global_load_lds_dwordx4 v[254:255], off
	s_mov_b32 m0, s78
	v_lshl_add_u64 v[254:255], v[200:201], 0, s[24:25]
	global_load_lds_dwordx4 v[254:255], off
	v_lshl_add_u64 v[254:255], v[202:203], 0, s[24:25]
	s_mov_b32 m0, s79
	s_nop 0
	global_load_lds_dwordx4 v[254:255], off
	s_add_u32 s44, s48, 0x40080
	s_addc_u32 s45, s49, 0
	s_add_i32 s48, s72, s7
	v_lshl_add_u64 v[254:255], s[44:45], 0, v[214:215]
	s_mov_b32 m0, s48
	s_nop 0
	global_load_lds_dwordx4 v[254:255], off
	v_lshl_add_u64 v[254:255], s[44:45], 0, v[210:211]
	s_add_i32 m0, s48, 0x2000
	s_nop 0
	global_load_lds_dwordx4 v[254:255], off
	s_waitcnt vmcnt(6)
	s_waitcnt lgkmcnt(0)
	s_barrier
	s_setprio 1
	v_mfma_f32_16x16x32_bf16 v[92:95], v[96:99], v[112:115], v[92:95]
	v_mfma_f32_16x16x32_bf16 v[28:31], v[104:107], v[112:115], v[28:31]
	v_mfma_f32_16x16x32_bf16 v[80:83], v[96:99], v[120:123], v[80:83]
	v_mfma_f32_16x16x32_bf16 v[16:19], v[104:107], v[120:123], v[16:19]
	v_mfma_f32_16x16x32_bf16 v[76:79], v[96:99], v[160:163], v[76:79]
	v_mfma_f32_16x16x32_bf16 v[12:15], v[104:107], v[160:163], v[12:15]
	v_mfma_f32_16x16x32_bf16 v[84:87], v[96:99], v[168:171], v[84:87]
	v_mfma_f32_16x16x32_bf16 v[20:23], v[104:107], v[168:171], v[20:23]
	v_mfma_f32_16x16x32_bf16 v[92:95], v[100:103], v[116:119], v[92:95]
	v_mfma_f32_16x16x32_bf16 v[28:31], v[108:111], v[116:119], v[28:31]
	v_mfma_f32_16x16x32_bf16 v[80:83], v[100:103], v[124:127], v[80:83]
	v_mfma_f32_16x16x32_bf16 v[16:19], v[108:111], v[124:127], v[16:19]
	v_mfma_f32_16x16x32_bf16 v[76:79], v[100:103], v[164:167], v[76:79]
	v_mfma_f32_16x16x32_bf16 v[12:15], v[108:111], v[164:167], v[12:15]
	v_mfma_f32_16x16x32_bf16 v[84:87], v[100:103], v[172:175], v[84:87]
	v_mfma_f32_16x16x32_bf16 v[20:23], v[108:111], v[172:175], v[20:23]
	v_mfma_f32_16x16x32_bf16 v[88:91], v[180:183], v[112:115], v[88:91]
	v_mfma_f32_16x16x32_bf16 v[24:27], v[188:191], v[112:115], v[24:27]
	v_mfma_f32_16x16x32_bf16 v[68:71], v[180:183], v[120:123], v[68:71]
	v_mfma_f32_16x16x32_bf16 v[4:7], v[188:191], v[120:123], v[4:7]
	v_mfma_f32_16x16x32_bf16 v[64:67], v[180:183], v[160:163], v[64:67]
	v_mfma_f32_16x16x32_bf16 v[0:3], v[188:191], v[160:163], v[0:3]
	v_mfma_f32_16x16x32_bf16 v[72:75], v[180:183], v[168:171], v[72:75]
	v_mfma_f32_16x16x32_bf16 v[8:11], v[188:191], v[168:171], v[8:11]
	v_mfma_f32_16x16x32_bf16 v[88:91], v[184:187], v[116:119], v[88:91]
	v_mfma_f32_16x16x32_bf16 v[24:27], v[192:195], v[116:119], v[24:27]
	v_mfma_f32_16x16x32_bf16 v[68:71], v[184:187], v[124:127], v[68:71]
	v_mfma_f32_16x16x32_bf16 v[4:7], v[192:195], v[124:127], v[4:7]
	v_mfma_f32_16x16x32_bf16 v[64:67], v[184:187], v[164:167], v[64:67]
	v_mfma_f32_16x16x32_bf16 v[0:3], v[192:195], v[164:167], v[0:3]
	v_mfma_f32_16x16x32_bf16 v[72:75], v[184:187], v[172:175], v[72:75]
	v_mfma_f32_16x16x32_bf16 v[8:11], v[192:195], v[172:175], v[8:11]
	s_setprio 0
	s_add_i32 s87, s87, 2
	s_add_u32 s85, s85, 0x100
	s_addc_u32 s86, s86, 0
	s_cmp_gt_u32 s87, 13
	s_mov_b64 s[44:45], s[46:47]
	s_barrier
	s_cbranch_scc0 .LBB0_1359
	s_lshl_b32 s44, s43, 7
	s_ashr_i32 s45, s44, 31
	s_lshl_b64 s[46:47], s[44:45], 2
	v_lshl_add_u64 v[96:97], v[220:221], 0, s[46:47]
	v_add_co_u32_e32 v100, vcc, 0x5000, v96
	v_lshl_add_u64 v[98:99], v[222:223], 0, s[46:47]
	s_nop 0
	v_addc_co_u32_e32 v101, vcc, 0, v97, vcc
	v_add_co_u32_e32 v102, vcc, 0xb000, v96
	global_load_dwordx4 v[160:163], v[96:97], off
	s_nop 0
	v_addc_co_u32_e32 v103, vcc, 0, v97, vcc
	global_load_dwordx4 v[164:167], v[100:101], off offset:2048
	global_load_dwordx4 v[168:171], v[102:103], off
	global_load_dwordx4 v[172:175], v[98:99], off
	v_add_co_u32_e32 v100, vcc, s76, v96
	s_nop 1
	v_addc_co_u32_e32 v101, vcc, 0, v97, vcc
	v_add_co_u32_e32 v102, vcc, 0x8000, v96
	s_nop 1
	v_addc_co_u32_e32 v103, vcc, 0, v97, vcc
	v_add_co_u32_e32 v96, vcc, 0xd000, v96
	global_load_dwordx4 v[176:179], v[100:101], off offset:3072
	global_load_dwordx4 v[180:183], v[102:103], off offset:1024
	v_addc_co_u32_e32 v97, vcc, 0, v97, vcc
	global_load_dwordx4 v[184:187], v[96:97], off offset:3072
	v_add_co_u32_e32 v96, vcc, 0x2000, v98
	s_nop 1
	v_addc_co_u32_e32 v97, vcc, 0, v99, vcc
	global_load_dwordx4 v[188:191], v[96:97], off offset:3072
	s_and_saveexec_b64 s[46:47], s[10:11]
	s_cbranch_execz .LBB0_1362
	ds_write_b128 v237, v[136:139]
	ds_write_b128 v237, v[148:151] offset:1024
	ds_write_b128 v237, v[40:43] offset:16
	ds_write_b128 v237, v[52:55] offset:1040
	ds_write_b128 v237, v[128:131] offset:512
	ds_write_b128 v237, v[140:143] offset:1536
	ds_write_b128 v237, v[32:35] offset:528
	ds_write_b128 v237, v[44:47] offset:1552
	ds_write_b128 v237, v[76:79] offset:4096
	ds_write_b128 v237, v[84:87] offset:5120
	ds_write_b128 v237, v[12:15] offset:4112
	ds_write_b128 v237, v[20:23] offset:5136
	ds_write_b128 v237, v[64:67] offset:4608
	ds_write_b128 v237, v[72:75] offset:5632
	ds_write_b128 v237, v[0:3] offset:4624
	ds_write_b128 v237, v[8:11] offset:5648

; #define PG8_STAGE(bufoff, gbase, voff) do { _Pragma("unroll") for (int _i = 0; _i < 2; ++_i) \
;         __builtin_amdgcn_global_load_lds((const unsigned*)((const char*)(gbase) + (voff)[_i]), (LAS unsigned*)(lds + (bufoff) + ldsw + _i * 8192), 16, 0, 0); } while (0)
; #define PG8_LDA(dst, b, h) do { _Pragma("unroll") for (int m = 0; m < 4; ++m) _Pragma("unroll") for (int k = 0; k < 2; ++k) dst[m][k] = *(const LAS bf16x8*)(lds + PG8_SA(b, h) + aoff + m * 2048 + k * 1024); } while (0)
; #define PG8_LDB(dst, b, h) do { _Pragma("unroll") for (int n = 0; n < 2; ++n) _Pragma("unroll") for (int k = 0; k < 2; ++k) dst[n][k] = *(const LAS bf16x8*)(lds + PG8_SB(b, h) + boff + n * 2048 + k * 1024); } while (0)
; #define PG8_MMA(ai, bj, At, Bt) do { __builtin_amdgcn_s_setprio(1); _Pragma("unroll") for (int m = 0; m < 4; ++m) _Pragma("unroll") for (int n = 0; n < 2; ++n) _Pragma("unroll") for (int k = 0; k < 2; ++k) \
;         acc[ai][bj][m][n] = __builtin_amdgcn_mfma_f32_16x16x32_bf16(Bt[n][k], At[m][k], acc[ai][bj][m][n], 0, 0, 0); __builtin_amdgcn_s_setprio(0); } while (0)
; #define PG8_WAIT_V(n) asm volatile("s_waitcnt vmcnt(" #n ")" ::: "memory")
; #define PG8_WAIT_L(n) asm volatile("s_waitcnt lgkmcnt(" #n ")" ::: "memory")
; template <class Epi>
; __device__ __forceinline__ void gemm_phase(LAS unsigned char* lds, const Gemm g, const StaticOrder& S, const Epi& E) {
;     ...
;         for (int t = 0; t < nt; t += 2) {
;             const bool last = (t == nt - 2);
;             const char* a1 = cA + (size_t)(t + 1) * kstep;
;             const char* a2 = last ? nA : cA + (size_t)(t + 2) * kstep; const char* b2 = last ? nB : cB + (size_t)(t + 2) * kstep;
;             const char* a3 = a2 + kstep; const char* b3 = b2 + kstep;
;             PG8_LDB(B0, 0, 0); PG8_SCHED; PG8_LDA(At, 0, 0); PG8_STAGE(PG8_SA(1, 1), a1 + hstepA, voffA);
;             PG8_WAIT_L(8); PG8_BAR; PG8_WAIT_L(0); PG8_MMA(0, 0, At, B0); PG8_BAR; PG8_SCHED;
;             PG8_LDB(B1, 0, 1); PG8_STAGE(PG8_SB(0, 0), b2, voffB);
;             PG8_BAR; PG8_WAIT_L(0); PG8_MMA(0, 1, At, B1); PG8_BAR;
;             PG8_LDA(At, 0, 1); PG8_STAGE(PG8_SA(0, 0), a2, voffA);
;             PG8_BAR; PG8_WAIT_L(0); PG8_MMA(1, 0, At, B0); PG8_BAR; PG8_SCHED;
;             PG8_STAGE(PG8_SB(0, 1), b2 + hstepB, voffB);
;             PG8_WAIT_V(6); PG8_BAR; PG8_MMA(1, 1, At, B1); PG8_BAR;
.LBB0_1940:
	ds_read_b128 v[96:99], v242
	ds_read_b128 v[100:103], v242 offset:1024
	ds_read_b128 v[104:107], v242 offset:2048
	ds_read_b128 v[108:111], v242 offset:3072
	s_add_u32 s38, s36, 0x100
	s_addc_u32 s39, s37, 0
	s_cmp_eq_u32 s72, 12
	s_cselect_b32 s43, s27, s39
	s_cselect_b32 s42, s68, s38
	s_cselect_b32 s41, s25, s71
	s_cselect_b32 s40, s69, s70
	v_lshl_add_u64 v[176:177], s[36:37], 0, v[224:225]
	s_add_i32 m0, s45, 0xc000
	ds_read_b128 v[112:115], v243
	ds_read_b128 v[116:119], v243 offset:1024
	ds_read_b128 v[120:123], v243 offset:2048
	ds_read_b128 v[124:127], v243 offset:3072
	ds_read_b128 v[160:163], v243 offset:4096
	ds_read_b128 v[164:167], v243 offset:5120
	ds_read_b128 v[168:171], v243 offset:6144
	ds_read_b128 v[172:175], v243 offset:7168
	global_load_lds_dwordx4 v[176:177], off
	v_lshl_add_u64 v[176:177], s[36:37], 0, v[226:227]
	s_add_i32 m0, s45, 0xe000
	s_nop 0
	global_load_lds_dwordx4 v[176:177], off
	ds_read_b128 v[176:179], v244
	ds_read_b128 v[180:183], v244 offset:1024
	ds_read_b128 v[184:187], v244 offset:2048
	ds_read_b128 v[188:191], v244 offset:3072
	s_waitcnt lgkmcnt(0)
	s_barrier
	s_setprio 1
	v_mfma_f32_16x16x32_bf16 v[156:159], v[96:99], v[112:115], v[156:159]
	v_mfma_f32_16x16x32_bf16 v[60:63], v[104:107], v[112:115], v[60:63]
	v_mfma_f32_16x16x32_bf16 v[144:147], v[96:99], v[120:123], v[144:147]
	v_mfma_f32_16x16x32_bf16 v[48:51], v[104:107], v[120:123], v[48:51]
	v_mfma_f32_16x16x32_bf16 v[136:139], v[96:99], v[160:163], v[136:139]
	v_mfma_f32_16x16x32_bf16 v[40:43], v[104:107], v[160:163], v[40:43]
	v_mfma_f32_16x16x32_bf16 v[148:151], v[96:99], v[168:171], v[148:151]
	v_mfma_f32_16x16x32_bf16 v[52:55], v[104:107], v[168:171], v[52:55]
	v_mfma_f32_16x16x32_bf16 v[156:159], v[100:103], v[116:119], v[156:159]
	v_mfma_f32_16x16x32_bf16 v[60:63], v[108:111], v[116:119], v[60:63]
	v_mfma_f32_16x16x32_bf16 v[144:147], v[100:103], v[124:127], v[144:147]
	v_mfma_f32_16x16x32_bf16 v[48:51], v[108:111], v[124:127], v[48:51]
	v_mfma_f32_16x16x32_bf16 v[136:139], v[100:103], v[164:167], v[136:139]
	v_mfma_f32_16x16x32_bf16 v[40:43], v[108:111], v[164:167], v[40:43]
	v_mfma_f32_16x16x32_bf16 v[148:151], v[100:103], v[172:175], v[148:151]
	v_mfma_f32_16x16x32_bf16 v[52:55], v[108:111], v[172:175], v[52:55]
	v_mfma_f32_16x16x32_bf16 v[152:155], v[176:179], v[112:115], v[152:155]
	v_mfma_f32_16x16x32_bf16 v[56:59], v[184:187], v[112:115], v[56:59]
	v_mfma_f32_16x16x32_bf16 v[36:39], v[184:187], v[120:123], v[36:39]
	v_mfma_f32_16x16x32_bf16 v[32:35], v[184:187], v[160:163], v[32:35]
	v_mfma_f32_16x16x32_bf16 v[44:47], v[184:187], v[168:171], v[44:47]
	v_mfma_f32_16x16x32_bf16 v[152:155], v[180:183], v[116:119], v[152:155]
	v_mfma_f32_16x16x32_bf16 v[56:59], v[188:191], v[116:119], v[56:59]
	v_mfma_f32_16x16x32_bf16 v[112:115], v[176:179], v[120:123], v[132:135]
	v_mfma_f32_16x16x32_bf16 v[36:39], v[188:191], v[124:127], v[36:39]
	v_mfma_f32_16x16x32_bf16 v[116:119], v[176:179], v[160:163], v[128:131]
	v_mfma_f32_16x16x32_bf16 v[32:35], v[188:191], v[164:167], v[32:35]
	v_mfma_f32_16x16x32_bf16 v[120:123], v[176:179], v[168:171], v[140:143]
	v_mfma_f32_16x16x32_bf16 v[44:47], v[188:191], v[172:175], v[44:47]
	v_mfma_f32_16x16x32_bf16 v[112:115], v[180:183], v[124:127], v[112:115]
	v_mfma_f32_16x16x32_bf16 v[116:119], v[180:183], v[164:167], v[116:119]
	v_mfma_f32_16x16x32_bf16 v[120:123], v[180:183], v[172:175], v[120:123]
	s_setprio 0
	s_barrier
	s_nop 1
	ds_read_b128 v[124:127], v243 offset:16384
	ds_read_b128 v[128:131], v243 offset:17408
	ds_read_b128 v[132:135], v243 offset:18432
	ds_read_b128 v[140:143], v243 offset:19456
	ds_read_b128 v[160:163], v243 offset:20480
	ds_read_b128 v[164:167], v243 offset:21504
	ds_read_b128 v[168:171], v243 offset:22528
	ds_read_b128 v[172:175], v243 offset:23552
	s_add_i32 s36, s59, s7
	v_lshl_add_u64 v[196:197], s[40:41], 0, v[214:215]
	s_mov_b32 m0, s36
	s_nop 0
	global_load_lds_dwordx4 v[196:197], off
	v_lshl_add_u64 v[198:199], s[40:41], 0, v[210:211]
	s_add_i32 m0, s36, 0x2000
	s_nop 0
	global_load_lds_dwordx4 v[198:199], off
	s_mov_b32 m0, s45
	v_lshl_add_u64 v[200:201], s[42:43], 0, v[216:217]
	global_load_lds_dwordx4 v[200:201], off
	v_lshl_add_u64 v[202:203], s[42:43], 0, v[212:213]
	s_mov_b32 m0, s46
	s_nop 0
	global_load_lds_dwordx4 v[202:203], off
	s_add_u32 s36, s40, 0x40000
	s_addc_u32 s37, s41, 0
	s_add_i32 s73, s62, s7
	v_lshl_add_u64 v[254:255], s[36:37], 0, v[214:215]
	s_mov_b32 m0, s73
	s_nop 0
	global_load_lds_dwordx4 v[254:255], off
	v_lshl_add_u64 v[254:255], s[36:37], 0, v[210:211]
	s_add_i32 m0, s73, 0x2000
	s_nop 0
	global_load_lds_dwordx4 v[254:255], off
	s_waitcnt vmcnt(6)
	s_waitcnt lgkmcnt(0)
	s_barrier
; #define PG8_STAGE(bufoff, gbase, voff) do { _Pragma("unroll") for (int _i = 0; _i < 2; ++_i) \
;         __builtin_amdgcn_global_load_lds((const unsigned*)((const char*)(gbase) + (voff)[_i]), (LAS unsigned*)(lds + (bufoff) + ldsw + _i * 8192), 16, 0, 0); } while (0)
; #define PG8_LDA(dst, b, h) do { _Pragma("unroll") for (int m = 0; m < 4; ++m) _Pragma("unroll") for (int k = 0; k < 2; ++k) dst[m][k] = *(const LAS bf16x8*)(lds + PG8_SA(b, h) + aoff + m * 2048 + k * 1024); } while (0)
; #define PG8_LDB(dst, b, h) do { _Pragma("unroll") for (int n = 0; n < 2; ++n) _Pragma("unroll") for (int k = 0; k < 2; ++k) dst[n][k] = *(const LAS bf16x8*)(lds + PG8_SB(b, h) + boff + n * 2048 + k * 1024); } while (0)
; #define PG8_MMA(ai, bj, At, Bt) do { __builtin_amdgcn_s_setprio(1); _Pragma("unroll") for (int m = 0; m < 4; ++m) _Pragma("unroll") for (int n = 0; n < 2; ++n) _Pragma("unroll") for (int k = 0; k < 2; ++k) \
;         acc[ai][bj][m][n] = __builtin_amdgcn_mfma_f32_16x16x32_bf16(Bt[n][k], At[m][k], acc[ai][bj][m][n], 0, 0, 0); __builtin_amdgcn_s_setprio(0); } while (0)
; #define PG8_WAIT_V(n) asm volatile("s_waitcnt vmcnt(" #n ")" ::: "memory")
; #define PG8_WAIT_L(n) asm volatile("s_waitcnt lgkmcnt(" #n ")" ::: "memory")
; #define PG8_BAR __builtin_amdgcn_s_barrier()
; #define PG8_SCHED __builtin_amdgcn_sched_barrier(0)
; template <class Epi>
; __device__ __forceinline__ void gemm_phase(LAS unsigned char* lds, const Gemm g, const StaticOrder& S, const Epi& E) {
;     ...
;             PG8_BAR; PG8_WAIT_L(0); PG8_MMA(1, 0, At, B0); PG8_BAR; PG8_SCHED;
;             PG8_STAGE(PG8_SB(0, 1), b2 + hstepB, voffB);
;             PG8_WAIT_V(6); PG8_BAR; PG8_MMA(1, 1, At, B1); PG8_BAR;
;             PG8_LDB(B0, 1, 0); PG8_SCHED; PG8_LDA(At, 1, 0); PG8_STAGE(PG8_SA(0, 1), a2 + hstepA, voffA);
;             PG8_WAIT_L(8); PG8_BAR; PG8_WAIT_L(0); PG8_MMA(0, 0, At, B0); PG8_BAR; PG8_SCHED;
;             PG8_LDB(B1, 1, 1); PG8_STAGE(PG8_SB(1, 0), b3, voffB);
;             PG8_BAR; PG8_WAIT_L(0); PG8_MMA(0, 1, At, B1); PG8_BAR;
	s_setprio 1
	v_mfma_f32_16x16x32_bf16 v[92:95], v[96:99], v[124:127], v[92:95]
	v_mfma_f32_16x16x32_bf16 v[28:31], v[104:107], v[124:127], v[28:31]
	v_mfma_f32_16x16x32_bf16 v[80:83], v[96:99], v[132:135], v[80:83]
	v_mfma_f32_16x16x32_bf16 v[16:19], v[104:107], v[132:135], v[16:19]
	v_mfma_f32_16x16x32_bf16 v[76:79], v[96:99], v[160:163], v[76:79]
	v_mfma_f32_16x16x32_bf16 v[12:15], v[104:107], v[160:163], v[12:15]
	v_mfma_f32_16x16x32_bf16 v[84:87], v[96:99], v[168:171], v[84:87]
	v_mfma_f32_16x16x32_bf16 v[20:23], v[104:107], v[168:171], v[20:23]
	v_mfma_f32_16x16x32_bf16 v[92:95], v[100:103], v[128:131], v[92:95]
	v_mfma_f32_16x16x32_bf16 v[28:31], v[108:111], v[128:131], v[28:31]
	v_mfma_f32_16x16x32_bf16 v[80:83], v[100:103], v[140:143], v[80:83]
	v_mfma_f32_16x16x32_bf16 v[16:19], v[108:111], v[140:143], v[16:19]
	v_mfma_f32_16x16x32_bf16 v[76:79], v[100:103], v[164:167], v[76:79]
	v_mfma_f32_16x16x32_bf16 v[12:15], v[108:111], v[164:167], v[12:15]
	v_mfma_f32_16x16x32_bf16 v[84:87], v[100:103], v[172:175], v[84:87]
	v_mfma_f32_16x16x32_bf16 v[20:23], v[108:111], v[172:175], v[20:23]
	v_mfma_f32_16x16x32_bf16 v[88:91], v[176:179], v[124:127], v[88:91]
	v_mfma_f32_16x16x32_bf16 v[24:27], v[184:187], v[124:127], v[24:27]
	v_mfma_f32_16x16x32_bf16 v[68:71], v[176:179], v[132:135], v[68:71]
	v_mfma_f32_16x16x32_bf16 v[4:7], v[184:187], v[132:135], v[4:7]
	v_mfma_f32_16x16x32_bf16 v[64:67], v[176:179], v[160:163], v[64:67]
	v_mfma_f32_16x16x32_bf16 v[0:3], v[184:187], v[160:163], v[0:3]
	v_mfma_f32_16x16x32_bf16 v[72:75], v[176:179], v[168:171], v[72:75]
	v_mfma_f32_16x16x32_bf16 v[8:11], v[184:187], v[168:171], v[8:11]
	v_mfma_f32_16x16x32_bf16 v[88:91], v[180:183], v[128:131], v[88:91]
	v_mfma_f32_16x16x32_bf16 v[24:27], v[188:191], v[128:131], v[24:27]
	v_mfma_f32_16x16x32_bf16 v[68:71], v[180:183], v[140:143], v[68:71]
	v_mfma_f32_16x16x32_bf16 v[4:7], v[188:191], v[140:143], v[4:7]
	v_mfma_f32_16x16x32_bf16 v[64:67], v[180:183], v[164:167], v[64:67]
	v_mfma_f32_16x16x32_bf16 v[0:3], v[188:191], v[164:167], v[0:3]
	v_mfma_f32_16x16x32_bf16 v[72:75], v[180:183], v[172:175], v[72:75]
	v_mfma_f32_16x16x32_bf16 v[8:11], v[188:191], v[172:175], v[8:11]
	s_setprio 0
	s_add_i32 s73, 0, 0x18000
	v_add_u32_e32 v108, s73, v234
	s_barrier
	ds_read_b128 v[96:99], v108
	ds_read_b128 v[100:103], v108 offset:1024
	ds_read_b128 v[104:107], v108 offset:2048
	ds_read_b128 v[108:111], v108 offset:3072
	s_add_u32 s36, s42, 0x40000
	s_addc_u32 s37, s43, 0
	s_mov_b32 m0, s47
	v_lshl_add_u64 v[132:133], s[36:37], 0, v[216:217]
	ds_read_b128 v[124:127], v243 offset:32768
	ds_read_b128 v[128:131], v243 offset:33792
	ds_read_b128 v[140:143], v243 offset:34816
	ds_read_b128 v[160:163], v243 offset:35840
	ds_read_b128 v[164:167], v243 offset:36864
	ds_read_b128 v[168:171], v243 offset:37888
	ds_read_b128 v[172:175], v243 offset:38912
	ds_read_b128 v[176:179], v243 offset:39936
	global_load_lds_dwordx4 v[132:133], off
	v_lshl_add_u64 v[132:133], s[36:37], 0, v[212:213]
	s_mov_b32 m0, s48
	s_nop 0
	global_load_lds_dwordx4 v[132:133], off
	s_add_i32 s42, 0, 0x1c000
	v_add_u32_e32 v132, s42, v234
	ds_read_b128 v[180:183], v132
	ds_read_b128 v[184:187], v132 offset:1024
	ds_read_b128 v[188:191], v132 offset:2048
	ds_read_b128 v[192:195], v132 offset:3072
	s_waitcnt lgkmcnt(0)
	s_barrier
	s_setprio 1
	v_mfma_f32_16x16x32_bf16 v[132:135], v[96:99], v[124:127], v[156:159]
	v_mfma_f32_16x16x32_bf16 v[156:159], v[100:103], v[128:131], v[132:135]
	v_mfma_f32_16x16x32_bf16 v[132:135], v[96:99], v[140:143], v[144:147]
	v_mfma_f32_16x16x32_bf16 v[144:147], v[100:103], v[160:163], v[132:135]
	v_mfma_f32_16x16x32_bf16 v[132:135], v[96:99], v[164:167], v[136:139]
	v_mfma_f32_16x16x32_bf16 v[60:63], v[104:107], v[124:127], v[60:63]
	v_mfma_f32_16x16x32_bf16 v[48:51], v[104:107], v[140:143], v[48:51]
	v_mfma_f32_16x16x32_bf16 v[136:139], v[100:103], v[168:171], v[132:135]
	v_mfma_f32_16x16x32_bf16 v[40:43], v[104:107], v[164:167], v[40:43]
	v_mfma_f32_16x16x32_bf16 v[132:135], v[96:99], v[172:175], v[148:151]
	v_mfma_f32_16x16x32_bf16 v[52:55], v[104:107], v[172:175], v[52:55]
	v_mfma_f32_16x16x32_bf16 v[60:63], v[108:111], v[128:131], v[60:63]
	v_mfma_f32_16x16x32_bf16 v[48:51], v[108:111], v[160:163], v[48:51]
	v_mfma_f32_16x16x32_bf16 v[40:43], v[108:111], v[168:171], v[40:43]
	v_mfma_f32_16x16x32_bf16 v[148:151], v[100:103], v[176:179], v[132:135]
	v_mfma_f32_16x16x32_bf16 v[52:55], v[108:111], v[176:179], v[52:55]
	v_mfma_f32_16x16x32_bf16 v[132:135], v[180:183], v[124:127], v[152:155]
	v_mfma_f32_16x16x32_bf16 v[112:115], v[180:183], v[140:143], v[112:115]
	v_mfma_f32_16x16x32_bf16 v[152:155], v[184:187], v[128:131], v[132:135]
	v_mfma_f32_16x16x32_bf16 v[56:59], v[188:191], v[124:127], v[56:59]
	v_mfma_f32_16x16x32_bf16 v[132:135], v[184:187], v[160:163], v[112:115]
	v_mfma_f32_16x16x32_bf16 v[112:115], v[180:183], v[164:167], v[116:119]
	v_mfma_f32_16x16x32_bf16 v[56:59], v[192:195], v[128:131], v[56:59]
	v_mfma_f32_16x16x32_bf16 v[36:39], v[188:191], v[140:143], v[36:39]
	v_mfma_f32_16x16x32_bf16 v[128:131], v[184:187], v[168:171], v[112:115]
	v_mfma_f32_16x16x32_bf16 v[32:35], v[188:191], v[164:167], v[32:35]
	v_mfma_f32_16x16x32_bf16 v[112:115], v[180:183], v[172:175], v[120:123]
	v_mfma_f32_16x16x32_bf16 v[44:47], v[188:191], v[172:175], v[44:47]
	v_mfma_f32_16x16x32_bf16 v[36:39], v[192:195], v[160:163], v[36:39]
	v_mfma_f32_16x16x32_bf16 v[32:35], v[192:195], v[168:171], v[32:35]
	v_mfma_f32_16x16x32_bf16 v[140:143], v[184:187], v[176:179], v[112:115]
	v_mfma_f32_16x16x32_bf16 v[44:47], v[192:195], v[176:179], v[44:47]
	s_setprio 0
	s_barrier
; #define LAS __attribute__((address_space(3)))
; #define PG8_STAGE(bufoff, gbase, voff) do { _Pragma("unroll") for (int _i = 0; _i < 2; ++_i) \
;         __builtin_amdgcn_global_load_lds((const unsigned*)((const char*)(gbase) + (voff)[_i]), (LAS unsigned*)(lds + (bufoff) + ldsw + _i * 8192), 16, 0, 0); } while (0)
; #define PG8_LDA(dst, b, h) do { _Pragma("unroll") for (int m = 0; m < 4; ++m) _Pragma("unroll") for (int k = 0; k < 2; ++k) dst[m][k] = *(const LAS bf16x8*)(lds + PG8_SA(b, h) + aoff + m * 2048 + k * 1024); } while (0)
; #define PG8_LDB(dst, b, h) do { _Pragma("unroll") for (int n = 0; n < 2; ++n) _Pragma("unroll") for (int k = 0; k < 2; ++k) dst[n][k] = *(const LAS bf16x8*)(lds + PG8_SB(b, h) + boff + n * 2048 + k * 1024); } while (0)
; #define PG8_WAIT_V(n) asm volatile("s_waitcnt vmcnt(" #n ")" ::: "memory")
; template <class Epi>
; __device__ __forceinline__ void gemm_phase(LAS unsigned char* lds, const Gemm g, const StaticOrder& S, const Epi& E) {
;     ...
;             PG8_LDB(B1, 1, 1); PG8_STAGE(PG8_SB(1, 0), b3, voffB);
;             PG8_BAR; PG8_WAIT_L(0); PG8_MMA(0, 1, At, B1); PG8_BAR;
;             PG8_LDA(At, 1, 1); PG8_STAGE(PG8_SA(1, 0), a3, voffA);
;             PG8_BAR; PG8_WAIT_L(0); PG8_MMA(1, 0, At, B0); PG8_BAR; PG8_SCHED;
;             PG8_STAGE(PG8_SB(1, 1), b3 + hstepB, voffB);
;             PG8_WAIT_V(6); PG8_BAR; PG8_MMA(1, 1, At, B1); PG8_BAR;
;     __device__ __forceinline__ void operator()(AccRef acc, const Unit& u, int wr, int wc, int fr, int fq) const {
;     ...
;         { const float* cv = cw + 128 * u.pn + clb; const float* cg = cv + FH; const float* bp = cb + 128 * u.pn + clb;
;           cwv[0][0] = *(const f32x4*)(cv); cwv[0][1] = *(const f32x4*)(cv + F2); cwv[0][2] = *(const f32x4*)(cv + 2 * F2); cwv[0][3] = *(const f32x4*)(bp);
;           cwv[0][4] = *(const f32x4*)(cg); cwv[0][5] = *(const f32x4*)(cg + F2); cwv[0][6] = *(const f32x4*)(cg + 2 * F2); cwv[0][7] = *(const f32x4*)(bp + FH); }
;         if (fr == 15) {
; #pragma unroll
;             for (int ai = 0; ai < 2; ++ai)
; #pragma unroll
;                 for (int bj = 0; bj < 2; ++bj)
; #pragma unroll
;                     for (int n = 0; n < 2; ++n) { *(LAS f32x4*)(xch + ((ai * 2 + wr) * 2 + 0) * 256 + bj * 128 + clb + 4 * n) = acc[ai][bj][2][n]; *(LAS f32x4*)(xch + ((ai * 2 + wr) * 2 + 1) * 256 + bj * 128 + clb + 4 * n) = acc[ai][bj][3][n]; }
	s_nop 1
	ds_read_b128 v[112:115], v243 offset:49152
	ds_read_b128 v[116:119], v243 offset:50176
	ds_read_b128 v[120:123], v243 offset:51200
	ds_read_b128 v[124:127], v243 offset:52224
	ds_read_b128 v[160:163], v243 offset:53248
	ds_read_b128 v[164:167], v243 offset:54272
	ds_read_b128 v[168:171], v243 offset:55296
	ds_read_b128 v[172:175], v243 offset:56320
	s_add_i32 s36, s73, s7
	v_lshl_add_u64 v[254:255], v[196:197], 0, s[16:17]
	s_mov_b32 m0, s36
	s_nop 0
	global_load_lds_dwordx4 v[254:255], off
	v_lshl_add_u64 v[254:255], v[198:199], 0, s[16:17]
	s_add_i32 m0, s36, 0x2000
	s_nop 0
	global_load_lds_dwordx4 v[254:255], off
	s_mov_b32 m0, s57
	v_lshl_add_u64 v[254:255], v[200:201], 0, s[16:17]
	global_load_lds_dwordx4 v[254:255], off
	v_lshl_add_u64 v[254:255], v[202:203], 0, s[16:17]
	s_mov_b32 m0, s58
	s_nop 0
	global_load_lds_dwordx4 v[254:255], off
	s_add_u32 s36, s40, 0x40080
	s_addc_u32 s37, s41, 0
	s_add_i32 s40, s42, s7
	v_lshl_add_u64 v[254:255], s[36:37], 0, v[214:215]
	s_mov_b32 m0, s40
	s_nop 0
	global_load_lds_dwordx4 v[254:255], off
	v_lshl_add_u64 v[254:255], s[36:37], 0, v[210:211]
	s_add_i32 m0, s40, 0x2000
	s_nop 0
	global_load_lds_dwordx4 v[254:255], off
	s_waitcnt vmcnt(6)
	s_waitcnt lgkmcnt(0)
	s_barrier
	s_setprio 1
	v_mfma_f32_16x16x32_bf16 v[92:95], v[96:99], v[112:115], v[92:95]
	v_mfma_f32_16x16x32_bf16 v[28:31], v[104:107], v[112:115], v[28:31]
	v_mfma_f32_16x16x32_bf16 v[80:83], v[96:99], v[120:123], v[80:83]
	v_mfma_f32_16x16x32_bf16 v[16:19], v[104:107], v[120:123], v[16:19]
	v_mfma_f32_16x16x32_bf16 v[76:79], v[96:99], v[160:163], v[76:79]
	v_mfma_f32_16x16x32_bf16 v[12:15], v[104:107], v[160:163], v[12:15]
	v_mfma_f32_16x16x32_bf16 v[84:87], v[96:99], v[168:171], v[84:87]
	v_mfma_f32_16x16x32_bf16 v[20:23], v[104:107], v[168:171], v[20:23]
	v_mfma_f32_16x16x32_bf16 v[92:95], v[100:103], v[116:119], v[92:95]
	v_mfma_f32_16x16x32_bf16 v[28:31], v[108:111], v[116:119], v[28:31]
	v_mfma_f32_16x16x32_bf16 v[80:83], v[100:103], v[124:127], v[80:83]
	v_mfma_f32_16x16x32_bf16 v[16:19], v[108:111], v[124:127], v[16:19]
	v_mfma_f32_16x16x32_bf16 v[76:79], v[100:103], v[164:167], v[76:79]
	v_mfma_f32_16x16x32_bf16 v[12:15], v[108:111], v[164:167], v[12:15]
	v_mfma_f32_16x16x32_bf16 v[84:87], v[100:103], v[172:175], v[84:87]
	v_mfma_f32_16x16x32_bf16 v[20:23], v[108:111], v[172:175], v[20:23]
	v_mfma_f32_16x16x32_bf16 v[88:91], v[180:183], v[112:115], v[88:91]
	v_mfma_f32_16x16x32_bf16 v[24:27], v[188:191], v[112:115], v[24:27]
	v_mfma_f32_16x16x32_bf16 v[68:71], v[180:183], v[120:123], v[68:71]
	v_mfma_f32_16x16x32_bf16 v[4:7], v[188:191], v[120:123], v[4:7]
	v_mfma_f32_16x16x32_bf16 v[64:67], v[180:183], v[160:163], v[64:67]
	v_mfma_f32_16x16x32_bf16 v[0:3], v[188:191], v[160:163], v[0:3]
	v_mfma_f32_16x16x32_bf16 v[72:75], v[180:183], v[168:171], v[72:75]
	v_mfma_f32_16x16x32_bf16 v[8:11], v[188:191], v[168:171], v[8:11]
	v_mfma_f32_16x16x32_bf16 v[88:91], v[184:187], v[116:119], v[88:91]
	v_mfma_f32_16x16x32_bf16 v[24:27], v[192:195], v[116:119], v[24:27]
	v_mfma_f32_16x16x32_bf16 v[68:71], v[184:187], v[124:127], v[68:71]
	v_mfma_f32_16x16x32_bf16 v[4:7], v[192:195], v[124:127], v[4:7]
	v_mfma_f32_16x16x32_bf16 v[64:67], v[184:187], v[164:167], v[64:67]
	v_mfma_f32_16x16x32_bf16 v[0:3], v[192:195], v[164:167], v[0:3]
	v_mfma_f32_16x16x32_bf16 v[72:75], v[184:187], v[172:175], v[72:75]
	v_mfma_f32_16x16x32_bf16 v[8:11], v[192:195], v[172:175], v[8:11]
	s_setprio 0
	s_add_i32 s72, s72, 2
	s_add_u32 s70, s70, 0x100
	s_addc_u32 s71, s71, 0
	s_cmp_gt_u32 s72, 13
	s_mov_b64 s[36:37], s[38:39]
	s_barrier
	s_cbranch_scc0 .LBB0_1940
	s_lshl_b32 s36, s35, 7
	s_ashr_i32 s37, s36, 31
	s_lshl_b64 s[38:39], s[36:37], 2
	v_lshl_add_u64 v[96:97], v[220:221], 0, s[38:39]
	v_add_co_u32_e32 v100, vcc, 0x5000, v96
	v_lshl_add_u64 v[98:99], v[222:223], 0, s[38:39]
	s_nop 0
	v_addc_co_u32_e32 v101, vcc, 0, v97, vcc
	v_add_co_u32_e32 v102, vcc, 0xb000, v96
	global_load_dwordx4 v[160:163], v[96:97], off
	s_nop 0
	v_addc_co_u32_e32 v103, vcc, 0, v97, vcc
	global_load_dwordx4 v[164:167], v[100:101], off offset:2048
	global_load_dwordx4 v[168:171], v[102:103], off
	global_load_dwordx4 v[172:175], v[98:99], off
	v_add_co_u32_e32 v100, vcc, s49, v96
	s_nop 1
	v_addc_co_u32_e32 v101, vcc, 0, v97, vcc
	v_add_co_u32_e32 v102, vcc, 0x8000, v96
	s_nop 1
	v_addc_co_u32_e32 v103, vcc, 0, v97, vcc
	v_add_co_u32_e32 v96, vcc, 0xd000, v96
	global_load_dwordx4 v[176:179], v[100:101], off offset:3072
	global_load_dwordx4 v[180:183], v[102:103], off offset:1024
	v_addc_co_u32_e32 v97, vcc, 0, v97, vcc
	global_load_dwordx4 v[184:187], v[96:97], off offset:3072
	v_add_co_u32_e32 v96, vcc, 0x2000, v98
	s_nop 1
	v_addc_co_u32_e32 v97, vcc, 0, v99, vcc
	global_load_dwordx4 v[188:191], v[96:97], off offset:3072
	s_and_saveexec_b64 s[38:39], s[0:1]
	s_cbranch_execz .LBB0_1943
	ds_write_b128 v236, v[136:139]
	ds_write_b128 v236, v[148:151] offset:1024
	ds_write_b128 v236, v[40:43] offset:16
	ds_write_b128 v236, v[52:55] offset:1040
	ds_write_b128 v236, v[128:131] offset:512
	ds_write_b128 v236, v[140:143] offset:1536
	ds_write_b128 v236, v[32:35] offset:528
	ds_write_b128 v236, v[44:47] offset:1552
	ds_write_b128 v236, v[76:79] offset:4096
	ds_write_b128 v236, v[84:87] offset:5120
	ds_write_b128 v236, v[12:15] offset:4112
	ds_write_b128 v236, v[20:23] offset:5136
	ds_write_b128 v236, v[64:67] offset:4608
	ds_write_b128 v236, v[72:75] offset:5632
	ds_write_b128 v236, v[0:3] offset:4624
	ds_write_b128 v236, v[8:11] offset:5648

; #define LAS __attribute__((address_space(3)))
; __device__ __forceinline__ int otid() { int t = threadIdx.x; asm volatile("" : "+v"(t)); return t; }
; #define SYNC() xcd_barrier(bar)
; __global__ void __launch_bounds__(NTHREADS, 2) fwd_megakernel(Params P) {
;     extern __shared__ __attribute__((aligned(16))) unsigned char lds_raw[];
;     LAS unsigned char* lds = (LAS unsigned char*)lds_raw;
;     cg::grid_group grid = cg::this_grid();
;     unsigned char* ws = P.ws;
;     bf16_t* HN = (bf16_t*)(ws + WS_HN);
;     bf16_t* B0 = (bf16_t*)(ws + WS_BIG); bf16_t* B1 = (bf16_t*)(ws + WS_BIG + ACT); bf16_t* B2 = (bf16_t*)(ws + WS_BIG + 2 * ACT); bf16_t* B3 = (bf16_t*)(ws + WS_BIG + 3 * ACT); bf16_t* B4 = (bf16_t*)(ws + WS_BIG + 4 * ACT);
;     float* RAW = (float*)(ws + WS_RAW);
;     float* X = P.out;
;     const int G = gridDim.x, bx = blockIdx.x;
;     pg8::StaticOrder S;
;     volatile LAS unsigned* MISC = (volatile LAS unsigned*)(lds + MISC_OFF);
;     if (threadIdx.x < 2) MISC[threadIdx.x] = 0u;
;     __syncthreads();
;     const XcdBarrier bar = xcd_barrier_post((unsigned*)ws, MISC);
;     grid.sync();
;     ...
;     { const int tid__ = otid(); const int lane = tid__ & 63, wave = tid__ >> 6;
;       weights_phase(P, (LAS float*)(lds + wave * 8448), lane, 0, P.nitems_a, blockIdx.x * 8 + wave, gridDim.x * 8); }
;     rmsnorm_phase(P.in[0], P.in[1], HN);
;     SYNC();
;     ...
;     pool_phase(HN, B0);
;     SYNC();
;     { pg8::Gemm g{B0, (const bf16_t*)(ws + WS_WPOOL), T, 1024, 256, D, 256, 0, 512}; S.init(T, 1024, G, bx);
;       EpiRes E{P.in[0], X, P.in[5], P.in[4]}; pg8::gemm_phase(lds, g, S, E); }
;     SYNC();
;     FFN_BLOCK(0, true);
;     rmsnorm_phase(X, P.in[1] + 1 * D, HN);
;     SYNC();
;     s5_phase(P, HN, B0, lds);
;     SYNC();
;     { pg8::Gemm g{B0, (const bf16_t*)(ws + WS_WS5), T, 2048, 1024, D, D, 0, 0}; S.init(T, 2048, G, bx);
;       EpiGateRes E{X, P.in[15]}; pg8::gemm_phase(lds, g, S, E); }
;     SYNC();
;     FFN_BLOCK(1, true);
;     rmsnorm_phase(X, P.in[1] + 2 * D, HN);
;     SYNC();
;     { pg8::Gemm g{HN, (const bf16_t*)(ws + WS_WLIN), T, 2048, 1024, D, D, 0, 0}; S.init(T, 2048, G, bx);
;       EpiLruIn E{B0, B2, P.in[17], P.in[18], (float*)(ws + WS_RAWL), (LAS float*)(lds + XCH_OFF)}; pg8::gemm_phase(lds, g, S, E); }
;     SYNC();
;     { pg8::Gemm g{B2, (const bf16_t*)(ws + WS_WGATE), T, 2048, 256, D, 256, 1, 512}; S.init(T, 2048, G, bx);
	.amdhsa_kernel _Z14fwd_megakernel6Params
		.amdhsa_group_segment_fixed_size 0
		.amdhsa_private_segment_fixed_size 0
		.amdhsa_kernarg_size 1864
		.amdhsa_user_sgpr_count 2
		.amdhsa_user_sgpr_dispatch_ptr 0
		.amdhsa_user_sgpr_queue_ptr 0
		.amdhsa_user_sgpr_kernarg_segment_ptr 1
		.amdhsa_user_sgpr_dispatch_id 0
		.amdhsa_user_sgpr_kernarg_preload_length 0
		.amdhsa_user_sgpr_kernarg_preload_offset 0
		.amdhsa_user_sgpr_private_segment_size 0
		.amdhsa_uses_dynamic_stack 0
		.amdhsa_enable_private_segment 0
		.amdhsa_system_sgpr_workgroup_id_x 1
		.amdhsa_system_sgpr_workgroup_id_y 0
		.amdhsa_system_sgpr_workgroup_id_z 0
		.amdhsa_system_sgpr_workgroup_info 0
		.amdhsa_system_vgpr_workitem_id 2
		.amdhsa_next_free_vgpr 256
		.amdhsa_next_free_sgpr 98
		.amdhsa_accum_offset 256
		.amdhsa_reserve_vcc 1
		.amdhsa_float_round_mode_32 0
		.amdhsa_float_round_mode_16_64 0
		.amdhsa_float_denorm_mode_32 3
		.amdhsa_float_denorm_mode_16_64 3
		.amdhsa_dx10_clamp 1
		.amdhsa_ieee_mode 1
		.amdhsa_fp16_overflow 0
		.amdhsa_tg_split 0
		.amdhsa_exception_fp_ieee_invalid_op 0
		.amdhsa_exception_fp_denorm_src 0
		.amdhsa_exception_fp_ieee_div_zero 0
		.amdhsa_exception_fp_ieee_overflow 0
		.amdhsa_exception_fp_ieee_underflow 0
		.amdhsa_exception_fp_ieee_inexact 0
		.amdhsa_exception_int_div_zero 0
	.end_amdhsa_kernel

; #define LAS __attribute__((address_space(3)))
; __device__ __forceinline__ int otid() { int t = threadIdx.x; asm volatile("" : "+v"(t)); return t; }
; #define SYNC() xcd_barrier(bar)
; __global__ void __launch_bounds__(NTHREADS, 2) fwd_megakernel(Params P) {
;     extern __shared__ __attribute__((aligned(16))) unsigned char lds_raw[];
;     LAS unsigned char* lds = (LAS unsigned char*)lds_raw;
;     cg::grid_group grid = cg::this_grid();
;     unsigned char* ws = P.ws;
;     bf16_t* HN = (bf16_t*)(ws + WS_HN);
;     bf16_t* B0 = (bf16_t*)(ws + WS_BIG); bf16_t* B1 = (bf16_t*)(ws + WS_BIG + ACT); bf16_t* B2 = (bf16_t*)(ws + WS_BIG + 2 * ACT); bf16_t* B3 = (bf16_t*)(ws + WS_BIG + 3 * ACT); bf16_t* B4 = (bf16_t*)(ws + WS_BIG + 4 * ACT);
;     float* RAW = (float*)(ws + WS_RAW);
;     float* X = P.out;
;     const int G = gridDim.x, bx = blockIdx.x;
;     pg8::StaticOrder S;
;     volatile LAS unsigned* MISC = (volatile LAS unsigned*)(lds + MISC_OFF);
;     if (threadIdx.x < 2) MISC[threadIdx.x] = 0u;
;     __syncthreads();
;     const XcdBarrier bar = xcd_barrier_post((unsigned*)ws, MISC);
;     grid.sync();
;     ...
;     { const int tid__ = otid(); const int lane = tid__ & 63, wave = tid__ >> 6;
;       weights_phase(P, (LAS float*)(lds + wave * 8448), lane, 0, P.nitems_a, blockIdx.x * 8 + wave, gridDim.x * 8); }
;     rmsnorm_phase(P.in[0], P.in[1], HN);
;     SYNC();
;     ...
;     pool_phase(HN, B0);
;     SYNC();
;     { pg8::Gemm g{B0, (const bf16_t*)(ws + WS_WPOOL), T, 1024, 256, D, 256, 0, 512}; S.init(T, 1024, G, bx);
;       EpiRes E{P.in[0], X, P.in[5], P.in[4]}; pg8::gemm_phase(lds, g, S, E); }
;     SYNC();
;     FFN_BLOCK(0, true);
;     rmsnorm_phase(X, P.in[1] + 1 * D, HN);
;     SYNC();
;     s5_phase(P, HN, B0, lds);
;     SYNC();
;     { pg8::Gemm g{B0, (const bf16_t*)(ws + WS_WS5), T, 2048, 1024, D, D, 0, 0}; S.init(T, 2048, G, bx);
;       EpiGateRes E{X, P.in[15]}; pg8::gemm_phase(lds, g, S, E); }
;     SYNC();
;     FFN_BLOCK(1, true);
;     rmsnorm_phase(X, P.in[1] + 2 * D, HN);
;     SYNC();
;     { pg8::Gemm g{HN, (const bf16_t*)(ws + WS_WLIN), T, 2048, 1024, D, D, 0, 0}; S.init(T, 2048, G, bx);
;       EpiLruIn E{B0, B2, P.in[17], P.in[18], (float*)(ws + WS_RAWL), (LAS float*)(lds + XCH_OFF)}; pg8::gemm_phase(lds, g, S, E); }
;     SYNC();
;     { pg8::Gemm g{B2, (const bf16_t*)(ws + WS_WGATE), T, 2048, 256, D, 256, 1, 512}; S.init(T, 2048, G, bx);
amdhsa.kernels:
  - .agpr_count:     0
    .args:
      - .offset:         0
        .size:           1608
        .value_kind:     by_value
      - .offset:         1608
        .size:           4
        .value_kind:     hidden_block_count_x
      - .offset:         1612
        .size:           4
        .value_kind:     hidden_block_count_y
      - .offset:         1616
        .size:           4
        .value_kind:     hidden_block_count_z
      - .offset:         1620
        .size:           2
        .value_kind:     hidden_group_size_x
      - .offset:         1622
        .size:           2
        .value_kind:     hidden_group_size_y
      - .offset:         1624
        .size:           2
        .value_kind:     hidden_group_size_z
      - .offset:         1626
        .size:           2
        .value_kind:     hidden_remainder_x
      - .offset:         1628
        .size:           2
        .value_kind:     hidden_remainder_y
      - .offset:         1630
        .size:           2
        .value_kind:     hidden_remainder_z
      - .offset:         1648
        .size:           8
        .value_kind:     hidden_global_offset_x
      - .offset:         1656
        .size:           8
        .value_kind:     hidden_global_offset_y
      - .offset:         1664
        .size:           8
        .value_kind:     hidden_global_offset_z
      - .offset:         1672
        .size:           2
        .value_kind:     hidden_grid_dims
      - .offset:         1696
        .size:           8
        .value_kind:     hidden_multigrid_sync_arg
      - .offset:         1728
        .size:           4
        .value_kind:     hidden_dynamic_lds_size
    .group_segment_fixed_size: 0
    .kernarg_segment_align: 8
    .kernarg_segment_size: 1864
    .language:       OpenCL C
    .language_version:
      - 2
      - 0
    .max_flat_workgroup_size: 512
    .name:           _Z14fwd_megakernel6Params
    .private_segment_fixed_size: 0
    .sgpr_count:     104
    .sgpr_spill_count: 10
    .symbol:         _Z14fwd_megakernel6Params.kd
    .uniform_work_group_size: 1
    .uses_dynamic_stack: false
    .vgpr_count:     256
    .vgpr_spill_count: 0
    .wavefront_size: 64
